# v1 + prologue-B BIAS rows: DPP wave reduction instead of 6-step ds_bpermute butterflies
# speedup vs baseline: 1.0150x; 1.0150x over previous
.LBB0_45:
	s_cmpk_gt_i32 s2, 0x4f
	s_mov_b64 s[12:13], -1
	s_cbranch_scc0 .LBB0_131
	s_add_i32 s17, s2, 0xffffffb0
	s_bfe_u32 s0, s17, 0xc0004
	s_mulk_i32 s0, 0xb22
	s_lshr_b32 s12, s0, 16
	s_mul_i32 s0, s12, 0x170
	s_sub_i32 s0, s17, s0
	s_lshl_b32 s0, s0, 3
	s_mul_i32 s60, s12, 0xf000
	s_mul_i32 s15, s12, 0xb80
	s_and_b32 s13, s0, 0xfff8
	v_lshl_add_u64 v[36:37], v[138:139], 0, s[60:61]
	s_add_i32 s14, s60, 0x9000
	s_add_i32 s60, s60, 0xc000
	s_add_i32 s15, s15, s13
	s_waitcnt lgkmcnt(0)
	v_lshl_add_u64 v[0:1], v[138:139], 0, s[60:61]
	s_lshl_b32 s60, s15, 11
	v_lshl_add_u64 v[90:91], v[140:141], 0, s[60:61]
	flat_load_dwordx4 v[82:85], v[90:91]
	flat_load_dwordx4 v[86:89], v[90:91] offset:16
	flat_load_dwordx4 v[76:79], v[36:37]
	flat_load_dwordx4 v[72:75], v[36:37] offset:16
	flat_load_dwordx4 v[68:71], v[36:37] offset:32
	flat_load_dwordx4 v[64:67], v[36:37] offset:48
	v_add_co_u32_e32 v44, vcc, 0x3000, v36
	s_mov_b64 s[18:19], 0x6000
	s_nop 0
	v_addc_co_u32_e32 v45, vcc, 0, v37, vcc
	s_mov_b32 s15, s61
	v_lshl_add_u64 v[38:39], v[36:37], 0, s[20:21]
	v_lshl_add_u64 v[92:93], v[36:37], 0, s[18:19]
	v_add_co_u32_e32 v36, vcc, 0x6000, v36
	v_lshl_add_u64 v[2:3], v[138:139], 0, s[14:15]
	s_nop 0
	v_addc_co_u32_e32 v37, vcc, 0, v37, vcc
	flat_load_dwordx4 v[56:59], v[38:39] offset:16
	flat_load_dwordx4 v[48:51], v[38:39] offset:32
	flat_load_dwordx4 v[40:43], v[92:93] offset:16
	flat_load_dwordx4 v[32:35], v[92:93] offset:32
	flat_load_dwordx4 v[28:31], v[2:3]
	flat_load_dwordx4 v[24:27], v[2:3] offset:16
	flat_load_dwordx4 v[20:23], v[2:3] offset:32
	flat_load_dwordx4 v[16:19], v[2:3] offset:48
	flat_load_dwordx4 v[12:15], v[0:1]
	flat_load_dwordx4 v[8:11], v[0:1] offset:16
	flat_load_dwordx4 v[4:7], v[0:1] offset:32
	s_nop 0
	flat_load_dwordx4 v[0:3], v[0:1] offset:48
	s_nop 0
	flat_load_dwordx4 v[60:63], v[44:45]
	flat_load_dwordx4 v[52:55], v[38:39] offset:48
	s_nop 0
	flat_load_dwordx4 v[44:47], v[36:37]
	s_nop 0
	flat_load_dwordx4 v[36:39], v[92:93] offset:48
	flat_load_dwordx4 v[134:137], v[90:91] offset:2048
	flat_load_dwordx4 v[130:133], v[90:91] offset:2064
	v_add_co_u32_e32 v92, vcc, s54, v90
	s_movk_i32 s0, 0x2000
	s_nop 0
	v_addc_co_u32_e32 v93, vcc, 0, v91, vcc
	v_add_co_u32_e32 v94, vcc, s0, v90
	s_mul_i32 s0, s12, 5
	s_nop 0
	v_addc_co_u32_e32 v95, vcc, 0, v91, vcc
	v_add_co_u32_e32 v162, vcc, s1, v90
	s_lshl_b32 s12, s13, 2
	s_nop 0
	v_addc_co_u32_e32 v163, vcc, 0, v91, vcc
	flat_load_dwordx4 v[126:129], v[92:93]
	flat_load_dwordx4 v[122:125], v[92:93] offset:16
	flat_load_dwordx4 v[118:121], v[92:93] offset:2048
	flat_load_dwordx4 v[114:117], v[92:93] offset:2064
	flat_load_dwordx4 v[110:113], v[94:95]
	flat_load_dwordx4 v[106:109], v[94:95] offset:16
	flat_load_dwordx4 v[102:105], v[94:95] offset:2048
	flat_load_dwordx4 v[98:101], v[94:95] offset:2064
	s_nop 0
	flat_load_dwordx4 v[94:97], v[162:163]
	flat_load_dwordx4 v[90:93], v[162:163] offset:16
	s_add_u32 s12, s3, s12
	s_addc_u32 s13, s16, 0
	s_mul_i32 s18, s0, 0x2e00
	s_waitcnt vmcnt(0) lgkmcnt(0)
	v_and_b32_e32 v158, 0xffff0000, v82
	v_and_b32_e32 v160, 0xffff0000, v83
	v_lshlrev_b32_e32 v154, 16, v82
	v_lshlrev_b32_e32 v156, 16, v83
	v_mul_f32_e32 v82, v77, v158
	v_mul_f32_e32 v83, v79, v160
	v_and_b32_e32 v159, 0xffff0000, v84
	v_and_b32_e32 v161, 0xffff0000, v85
	v_fmac_f32_e32 v82, v76, v154
	v_fmac_f32_e32 v83, v78, v156
	v_lshlrev_b32_e32 v155, 16, v84
	v_lshlrev_b32_e32 v157, 16, v85
	v_add_f32_e32 v82, v82, v83
	v_mul_f32_e32 v83, v73, v159
	v_mul_f32_e32 v84, v75, v161
	v_fmac_f32_e32 v83, v72, v155
	v_fmac_f32_e32 v84, v74, v157
	v_and_b32_e32 v147, 0xffff0000, v86
	v_and_b32_e32 v152, 0xffff0000, v87
	v_add_f32_e32 v82, 0, v82
	v_add_f32_e32 v83, v83, v84
	v_lshlrev_b32_e32 v80, 16, v86
	v_lshlrev_b32_e32 v145, 16, v87
	v_add_f32_e32 v82, v83, v82
	v_mul_f32_e32 v83, v69, v147
	v_mul_f32_e32 v84, v71, v152
	v_fmac_f32_e32 v83, v68, v80
	v_fmac_f32_e32 v84, v70, v145
	v_and_b32_e32 v151, 0xffff0000, v88
	v_and_b32_e32 v153, 0xffff0000, v89
	v_add_f32_e32 v83, v83, v84
	v_lshlrev_b32_e32 v143, 16, v88
	v_lshlrev_b32_e32 v146, 16, v89
	v_add_f32_e32 v164, v83, v82
	v_mul_f32_e32 v82, v65, v151
	v_mul_f32_e32 v83, v67, v153
	v_fmac_f32_e32 v82, v64, v143
	v_fmac_f32_e32 v83, v66, v146
	v_add_f32_e32 v165, v82, v83
	flat_load_dwordx4 v[86:89], v[162:163] offset:2048
	flat_load_dwordx4 v[82:85], v[162:163] offset:2064
	v_add_f32_e32 v162, v165, v164
	s_waitcnt lgkmcnt(0)
	s_nop 1
	v_add_f32_dpp v162, v162, v162 quad_perm:[1,0,3,2] row_mask:0xf bank_mask:0xf
	s_nop 1
	v_add_f32_dpp v162, v162, v162 quad_perm:[2,3,0,1] row_mask:0xf bank_mask:0xf
	s_nop 1
	v_add_f32_dpp v162, v162, v162 row_half_mirror row_mask:0xf bank_mask:0xf
	s_nop 1
	v_add_f32_dpp v162, v162, v162 row_mirror row_mask:0xf bank_mask:0xf
	s_nop 1
	v_readlane_b32 s100, v162, 16
	v_readlane_b32 s101, v162, 32
	s_nop 1
	v_add_f32_e32 v163, s100, v162
	v_readlane_b32 s100, v162, 48
	v_add_f32_e32 v163, s101, v163
	s_nop 1
	v_add_f32_e32 v162, s100, v163
	s_and_saveexec_b64 s[14:15], s[38:39]
	s_cbranch_execz .LBB0_48
	v_mov_b32_e32 v163, s18
	global_store_dword v163, v162, s[12:13] sc1
.LBB0_48:
	s_or_b64 exec, exec, s[14:15]
	v_mul_f32_e32 v162, v61, v158
	s_waitcnt lgkmcnt(0)
	v_mul_f32_e32 v163, v63, v160
	v_fmac_f32_e32 v162, v60, v154
	v_fmac_f32_e32 v163, v62, v156
	v_add_f32_e32 v162, v162, v163
	v_mul_f32_e32 v163, v57, v159
	v_mul_f32_e32 v164, v59, v161
	v_fmac_f32_e32 v163, v56, v155
	v_fmac_f32_e32 v164, v58, v157
	v_add_f32_e32 v162, 0, v162
	v_add_f32_e32 v163, v163, v164
	v_add_f32_e32 v162, v163, v162
	v_mul_f32_e32 v163, v49, v147
	v_mul_f32_e32 v164, v51, v152
	v_fmac_f32_e32 v163, v48, v80
	v_fmac_f32_e32 v164, v50, v145
	v_add_f32_e32 v163, v163, v164
	v_add_f32_e32 v162, v163, v162
	v_mul_f32_e32 v163, v53, v151
	v_mul_f32_e32 v164, v55, v153
	v_fmac_f32_e32 v163, v52, v143
	v_fmac_f32_e32 v164, v54, v146
	v_add_f32_e32 v163, v163, v164
	v_add_f32_e32 v162, v163, v162
	s_add_i32 s19, s0, 1
	s_mulk_i32 s19, 0x2e00
	s_waitcnt lgkmcnt(0)
	s_nop 1
	v_add_f32_dpp v162, v162, v162 quad_perm:[1,0,3,2] row_mask:0xf bank_mask:0xf
	s_nop 1
	v_add_f32_dpp v162, v162, v162 quad_perm:[2,3,0,1] row_mask:0xf bank_mask:0xf
	s_nop 1
	v_add_f32_dpp v162, v162, v162 row_half_mirror row_mask:0xf bank_mask:0xf
	s_nop 1
	v_add_f32_dpp v162, v162, v162 row_mirror row_mask:0xf bank_mask:0xf
	s_nop 1
	v_readlane_b32 s100, v162, 16
	v_readlane_b32 s101, v162, 32
	s_nop 1
	v_add_f32_e32 v163, s100, v162
	v_readlane_b32 s100, v162, 48
	v_add_f32_e32 v163, s101, v163
	s_nop 1
	v_add_f32_e32 v162, s100, v163
	s_and_saveexec_b64 s[14:15], s[38:39]
	s_cbranch_execz .LBB0_50
	v_mov_b32_e32 v163, s19
	global_store_dword v163, v162, s[12:13] sc1
.LBB0_50:
	s_or_b64 exec, exec, s[14:15]
	v_mul_f32_e32 v162, v45, v158
	s_waitcnt lgkmcnt(0)
	v_mul_f32_e32 v163, v47, v160
	v_fmac_f32_e32 v162, v44, v154
	v_fmac_f32_e32 v163, v46, v156
	v_add_f32_e32 v162, v162, v163
	v_mul_f32_e32 v163, v41, v159
	v_mul_f32_e32 v164, v43, v161
	v_fmac_f32_e32 v163, v40, v155
	v_fmac_f32_e32 v164, v42, v157
	v_add_f32_e32 v162, 0, v162
	v_add_f32_e32 v163, v163, v164
	v_add_f32_e32 v162, v163, v162
	v_mul_f32_e32 v163, v33, v147
	v_mul_f32_e32 v164, v35, v152
	v_fmac_f32_e32 v163, v32, v80
	v_fmac_f32_e32 v164, v34, v145
	v_add_f32_e32 v163, v163, v164
	v_add_f32_e32 v162, v163, v162
	v_mul_f32_e32 v163, v37, v151
	v_mul_f32_e32 v164, v39, v153
	v_fmac_f32_e32 v163, v36, v143
	v_fmac_f32_e32 v164, v38, v146
	v_add_f32_e32 v163, v163, v164
	v_add_f32_e32 v162, v163, v162
	s_add_i32 s26, s0, 2
	s_mulk_i32 s26, 0x2e00
	s_waitcnt lgkmcnt(0)
	s_nop 1
	v_add_f32_dpp v162, v162, v162 quad_perm:[1,0,3,2] row_mask:0xf bank_mask:0xf
	s_nop 1
	v_add_f32_dpp v162, v162, v162 quad_perm:[2,3,0,1] row_mask:0xf bank_mask:0xf
	s_nop 1
	v_add_f32_dpp v162, v162, v162 row_half_mirror row_mask:0xf bank_mask:0xf
	s_nop 1
	v_add_f32_dpp v162, v162, v162 row_mirror row_mask:0xf bank_mask:0xf
	s_nop 1
	v_readlane_b32 s100, v162, 16
	v_readlane_b32 s101, v162, 32
	s_nop 1
	v_add_f32_e32 v163, s100, v162
	v_readlane_b32 s100, v162, 48
	v_add_f32_e32 v163, s101, v163
	s_nop 1
	v_add_f32_e32 v162, s100, v163
	s_and_saveexec_b64 s[14:15], s[38:39]
	s_cbranch_execz .LBB0_52
	v_mov_b32_e32 v163, s26
	global_store_dword v163, v162, s[12:13] sc1
.LBB0_52:
	s_or_b64 exec, exec, s[14:15]
	v_mul_f32_e32 v162, v29, v158
	s_waitcnt lgkmcnt(0)
	v_mul_f32_e32 v163, v31, v160
	v_fmac_f32_e32 v162, v28, v154
	v_fmac_f32_e32 v163, v30, v156
	v_add_f32_e32 v162, v162, v163
	v_mul_f32_e32 v163, v25, v159
	v_mul_f32_e32 v164, v27, v161
	v_fmac_f32_e32 v163, v24, v155
	v_fmac_f32_e32 v164, v26, v157
	v_add_f32_e32 v162, 0, v162
	v_add_f32_e32 v163, v163, v164
	v_add_f32_e32 v162, v163, v162
	v_mul_f32_e32 v163, v21, v147
	v_mul_f32_e32 v164, v23, v152
	v_fmac_f32_e32 v163, v20, v80
	v_fmac_f32_e32 v164, v22, v145
	v_add_f32_e32 v163, v163, v164
	v_add_f32_e32 v162, v163, v162
	v_mul_f32_e32 v163, v17, v151
	v_mul_f32_e32 v164, v19, v153
	v_fmac_f32_e32 v163, v16, v143
	v_fmac_f32_e32 v164, v18, v146
	v_add_f32_e32 v163, v163, v164
	v_add_f32_e32 v162, v163, v162
	s_add_i32 s27, s0, 3
	s_mulk_i32 s27, 0x2e00
	s_waitcnt lgkmcnt(0)
	s_nop 1
	v_add_f32_dpp v162, v162, v162 quad_perm:[1,0,3,2] row_mask:0xf bank_mask:0xf
	s_nop 1
	v_add_f32_dpp v162, v162, v162 quad_perm:[2,3,0,1] row_mask:0xf bank_mask:0xf
	s_nop 1
	v_add_f32_dpp v162, v162, v162 row_half_mirror row_mask:0xf bank_mask:0xf
	s_nop 1
	v_add_f32_dpp v162, v162, v162 row_mirror row_mask:0xf bank_mask:0xf
	s_nop 1
	v_readlane_b32 s100, v162, 16
	v_readlane_b32 s101, v162, 32
	s_nop 1
	v_add_f32_e32 v163, s100, v162
	v_readlane_b32 s100, v162, 48
	v_add_f32_e32 v163, s101, v163
	s_nop 1
	v_add_f32_e32 v162, s100, v163
	s_and_saveexec_b64 s[14:15], s[38:39]
	s_cbranch_execz .LBB0_54
	v_mov_b32_e32 v163, s27
	global_store_dword v163, v162, s[12:13] sc1
.LBB0_54:
	s_or_b64 exec, exec, s[14:15]
	v_mul_f32_e32 v158, v13, v158
	v_fmac_f32_e32 v158, v12, v154
	v_mul_f32_e32 v154, v15, v160
	v_fmac_f32_e32 v154, v14, v156
	v_mul_f32_e32 v156, v9, v159
	v_mul_f32_e32 v147, v5, v147
	v_fmac_f32_e32 v156, v8, v155
	v_mul_f32_e32 v155, v11, v161
	v_fmac_f32_e32 v147, v4, v80
	v_mul_f32_e32 v80, v7, v152
	v_add_f32_e32 v154, v158, v154
	v_fmac_f32_e32 v155, v10, v157
	v_fmac_f32_e32 v80, v6, v145
	v_mul_f32_e32 v145, v1, v151
	v_add_f32_e32 v154, 0, v154
	v_add_f32_e32 v155, v156, v155
	v_fmac_f32_e32 v145, v0, v143
	v_mul_f32_e32 v143, v3, v153
	v_add_f32_e32 v154, v155, v154
	v_add_f32_e32 v80, v147, v80
	v_fmac_f32_e32 v143, v2, v146
	v_add_f32_e32 v80, v80, v154
	v_add_f32_e32 v143, v145, v143
	v_add_f32_e32 v80, v143, v80
	s_add_i32 s28, s0, 4
	s_mulk_i32 s28, 0x2e00
	s_waitcnt lgkmcnt(0)
	s_nop 1
	v_add_f32_dpp v80, v80, v80 quad_perm:[1,0,3,2] row_mask:0xf bank_mask:0xf
	s_nop 1
	v_add_f32_dpp v80, v80, v80 quad_perm:[2,3,0,1] row_mask:0xf bank_mask:0xf
	s_nop 1
	v_add_f32_dpp v80, v80, v80 row_half_mirror row_mask:0xf bank_mask:0xf
	s_nop 1
	v_add_f32_dpp v80, v80, v80 row_mirror row_mask:0xf bank_mask:0xf
	s_nop 1
	v_readlane_b32 s100, v80, 16
	v_readlane_b32 s101, v80, 32
	s_nop 1
	v_add_f32_e32 v143, s100, v80
	v_readlane_b32 s100, v80, 48
	v_add_f32_e32 v143, s101, v143
	s_nop 1
	v_add_f32_e32 v80, s100, v143
	s_and_saveexec_b64 s[14:15], s[38:39]
	s_cbranch_execz .LBB0_56
	v_mov_b32_e32 v143, s28
	global_store_dword v143, v80, s[12:13] sc1
.LBB0_56:
	s_or_b64 exec, exec, s[14:15]
	v_and_b32_e32 v151, 0xffff0000, v134
	v_and_b32_e32 v153, 0xffff0000, v135
	v_lshlrev_b32_e32 v145, 16, v134
	v_lshlrev_b32_e32 v147, 16, v135
	v_mul_f32_e32 v154, v77, v151
	v_mul_f32_e32 v155, v79, v153
	v_lshlrev_b32_e32 v146, 16, v136
	v_and_b32_e32 v152, 0xffff0000, v136
	v_lshlrev_b32_e32 v136, 16, v137
	v_and_b32_e32 v137, 0xffff0000, v137
	v_fmac_f32_e32 v154, v76, v145
	v_fmac_f32_e32 v155, v78, v147
	v_add_f32_e32 v154, v154, v155
	v_mul_f32_e32 v155, v73, v152
	v_mul_f32_e32 v156, v75, v137
	v_fmac_f32_e32 v155, v72, v146
	v_fmac_f32_e32 v156, v74, v136
	s_waitcnt lgkmcnt(0)
	v_and_b32_e32 v143, 0xffff0000, v130
	v_and_b32_e32 v135, 0xffff0000, v131
	v_add_f32_e32 v154, 0, v154
	v_add_f32_e32 v155, v155, v156
	v_lshlrev_b32_e32 v80, 16, v130
	v_lshlrev_b32_e32 v134, 16, v131
	v_add_f32_e32 v154, v155, v154
	v_mul_f32_e32 v155, v69, v143
	v_mul_f32_e32 v156, v71, v135
	v_fmac_f32_e32 v155, v68, v80
	v_fmac_f32_e32 v156, v70, v134
	v_lshlrev_b32_e32 v130, 16, v132
	v_and_b32_e32 v132, 0xffff0000, v132
	v_lshlrev_b32_e32 v131, 16, v133
	v_and_b32_e32 v133, 0xffff0000, v133
	v_add_f32_e32 v155, v155, v156
	v_add_f32_e32 v154, v155, v154
	v_mul_f32_e32 v155, v65, v132
	v_mul_f32_e32 v156, v67, v133
	v_fmac_f32_e32 v155, v64, v130
	v_fmac_f32_e32 v156, v66, v131
	v_add_f32_e32 v155, v155, v156
	v_add_f32_e32 v154, v155, v154
	s_waitcnt lgkmcnt(0)
	s_nop 1
	v_add_f32_dpp v154, v154, v154 quad_perm:[1,0,3,2] row_mask:0xf bank_mask:0xf
	s_nop 1
	v_add_f32_dpp v154, v154, v154 quad_perm:[2,3,0,1] row_mask:0xf bank_mask:0xf
	s_nop 1
	v_add_f32_dpp v154, v154, v154 row_half_mirror row_mask:0xf bank_mask:0xf
	s_nop 1
	v_add_f32_dpp v154, v154, v154 row_mirror row_mask:0xf bank_mask:0xf
	s_nop 1
	v_readlane_b32 s100, v154, 16
	v_readlane_b32 s101, v154, 32
	s_nop 1
	v_add_f32_e32 v155, s100, v154
	v_readlane_b32 s100, v154, 48
	v_add_f32_e32 v155, s101, v155
	s_nop 1
	v_add_f32_e32 v154, s100, v155
	s_and_saveexec_b64 s[14:15], s[38:39]
	s_cbranch_execz .LBB0_58
	v_mov_b32_e32 v155, s18
	global_store_dword v155, v154, s[12:13] offset:4 sc1
.LBB0_58:
	s_or_b64 exec, exec, s[14:15]
	v_mul_f32_e32 v154, v61, v151
	s_waitcnt lgkmcnt(0)
	v_mul_f32_e32 v155, v63, v153
	v_fmac_f32_e32 v154, v60, v145
	v_fmac_f32_e32 v155, v62, v147
	v_add_f32_e32 v154, v154, v155
	v_mul_f32_e32 v155, v57, v152
	v_mul_f32_e32 v156, v59, v137
	v_fmac_f32_e32 v155, v56, v146
	v_fmac_f32_e32 v156, v58, v136
	v_add_f32_e32 v154, 0, v154
	v_add_f32_e32 v155, v155, v156
	v_add_f32_e32 v154, v155, v154
	v_mul_f32_e32 v155, v49, v143
	v_mul_f32_e32 v156, v51, v135
	v_fmac_f32_e32 v155, v48, v80
	v_fmac_f32_e32 v156, v50, v134
	v_add_f32_e32 v155, v155, v156
	v_add_f32_e32 v154, v155, v154
	v_mul_f32_e32 v155, v53, v132
	v_mul_f32_e32 v156, v55, v133
	v_fmac_f32_e32 v155, v52, v130
	v_fmac_f32_e32 v156, v54, v131
	v_add_f32_e32 v155, v155, v156
	v_add_f32_e32 v154, v155, v154
	s_waitcnt lgkmcnt(0)
	s_nop 1
	v_add_f32_dpp v154, v154, v154 quad_perm:[1,0,3,2] row_mask:0xf bank_mask:0xf
	s_nop 1
	v_add_f32_dpp v154, v154, v154 quad_perm:[2,3,0,1] row_mask:0xf bank_mask:0xf
	s_nop 1
	v_add_f32_dpp v154, v154, v154 row_half_mirror row_mask:0xf bank_mask:0xf
	s_nop 1
	v_add_f32_dpp v154, v154, v154 row_mirror row_mask:0xf bank_mask:0xf
	s_nop 1
	v_readlane_b32 s100, v154, 16
	v_readlane_b32 s101, v154, 32
	s_nop 1
	v_add_f32_e32 v155, s100, v154
	v_readlane_b32 s100, v154, 48
	v_add_f32_e32 v155, s101, v155
	s_nop 1
	v_add_f32_e32 v154, s100, v155
	s_and_saveexec_b64 s[14:15], s[38:39]
	s_cbranch_execz .LBB0_60
	v_mov_b32_e32 v155, s19
	global_store_dword v155, v154, s[12:13] offset:4 sc1
.LBB0_60:
	s_or_b64 exec, exec, s[14:15]
	v_mul_f32_e32 v154, v45, v151
	s_waitcnt lgkmcnt(0)
	v_mul_f32_e32 v155, v47, v153
	v_fmac_f32_e32 v154, v44, v145
	v_fmac_f32_e32 v155, v46, v147
	v_add_f32_e32 v154, v154, v155
	v_mul_f32_e32 v155, v41, v152
	v_mul_f32_e32 v156, v43, v137
	v_fmac_f32_e32 v155, v40, v146
	v_fmac_f32_e32 v156, v42, v136
	v_add_f32_e32 v154, 0, v154
	v_add_f32_e32 v155, v155, v156
	v_add_f32_e32 v154, v155, v154
	v_mul_f32_e32 v155, v33, v143
	v_mul_f32_e32 v156, v35, v135
	v_fmac_f32_e32 v155, v32, v80
	v_fmac_f32_e32 v156, v34, v134
	v_add_f32_e32 v155, v155, v156
	v_add_f32_e32 v154, v155, v154
	v_mul_f32_e32 v155, v37, v132
	v_mul_f32_e32 v156, v39, v133
	v_fmac_f32_e32 v155, v36, v130
	v_fmac_f32_e32 v156, v38, v131
	v_add_f32_e32 v155, v155, v156
	v_add_f32_e32 v154, v155, v154
	s_waitcnt lgkmcnt(0)
	s_nop 1
	v_add_f32_dpp v154, v154, v154 quad_perm:[1,0,3,2] row_mask:0xf bank_mask:0xf
	s_nop 1
	v_add_f32_dpp v154, v154, v154 quad_perm:[2,3,0,1] row_mask:0xf bank_mask:0xf
	s_nop 1
	v_add_f32_dpp v154, v154, v154 row_half_mirror row_mask:0xf bank_mask:0xf
	s_nop 1
	v_add_f32_dpp v154, v154, v154 row_mirror row_mask:0xf bank_mask:0xf
	s_nop 1
	v_readlane_b32 s100, v154, 16
	v_readlane_b32 s101, v154, 32
	s_nop 1
	v_add_f32_e32 v155, s100, v154
	v_readlane_b32 s100, v154, 48
	v_add_f32_e32 v155, s101, v155
	s_nop 1
	v_add_f32_e32 v154, s100, v155
	s_and_saveexec_b64 s[14:15], s[38:39]
	s_cbranch_execz .LBB0_62
	v_mov_b32_e32 v155, s26
	global_store_dword v155, v154, s[12:13] offset:4 sc1
.LBB0_62:
	s_or_b64 exec, exec, s[14:15]
	v_mul_f32_e32 v154, v29, v151
	s_waitcnt lgkmcnt(0)
	v_mul_f32_e32 v155, v31, v153
	v_fmac_f32_e32 v154, v28, v145
	v_fmac_f32_e32 v155, v30, v147
	v_add_f32_e32 v154, v154, v155
	v_mul_f32_e32 v155, v25, v152
	v_mul_f32_e32 v156, v27, v137
	v_fmac_f32_e32 v155, v24, v146
	v_fmac_f32_e32 v156, v26, v136
	v_add_f32_e32 v154, 0, v154
	v_add_f32_e32 v155, v155, v156
	v_add_f32_e32 v154, v155, v154
	v_mul_f32_e32 v155, v21, v143
	v_mul_f32_e32 v156, v23, v135
	v_fmac_f32_e32 v155, v20, v80
	v_fmac_f32_e32 v156, v22, v134
	v_add_f32_e32 v155, v155, v156
	v_add_f32_e32 v154, v155, v154
	v_mul_f32_e32 v155, v17, v132
	v_mul_f32_e32 v156, v19, v133
	v_fmac_f32_e32 v155, v16, v130
	v_fmac_f32_e32 v156, v18, v131
	v_add_f32_e32 v155, v155, v156
	v_add_f32_e32 v154, v155, v154
	s_waitcnt lgkmcnt(0)
	s_nop 1
	v_add_f32_dpp v154, v154, v154 quad_perm:[1,0,3,2] row_mask:0xf bank_mask:0xf
	s_nop 1
	v_add_f32_dpp v154, v154, v154 quad_perm:[2,3,0,1] row_mask:0xf bank_mask:0xf
	s_nop 1
	v_add_f32_dpp v154, v154, v154 row_half_mirror row_mask:0xf bank_mask:0xf
	s_nop 1
	v_add_f32_dpp v154, v154, v154 row_mirror row_mask:0xf bank_mask:0xf
	s_nop 1
	v_readlane_b32 s100, v154, 16
	v_readlane_b32 s101, v154, 32
	s_nop 1
	v_add_f32_e32 v155, s100, v154
	v_readlane_b32 s100, v154, 48
	v_add_f32_e32 v155, s101, v155
	s_nop 1
	v_add_f32_e32 v154, s100, v155
	s_and_saveexec_b64 s[14:15], s[38:39]
	s_cbranch_execz .LBB0_64
	v_mov_b32_e32 v155, s27
	global_store_dword v155, v154, s[12:13] offset:4 sc1
.LBB0_64:
	s_or_b64 exec, exec, s[14:15]
	v_mul_f32_e32 v151, v13, v151
	v_fmac_f32_e32 v151, v12, v145
	v_mul_f32_e32 v145, v15, v153
	v_fmac_f32_e32 v145, v14, v147
	v_mul_f32_e32 v147, v9, v152
	v_mul_f32_e32 v137, v11, v137
	v_fmac_f32_e32 v147, v8, v146
	v_fmac_f32_e32 v137, v10, v136
	v_add_f32_e32 v136, v147, v137
	v_mul_f32_e32 v137, v5, v143
	v_add_f32_e32 v145, v151, v145
	v_fmac_f32_e32 v137, v4, v80
	v_mul_f32_e32 v80, v7, v135
	v_mul_f32_e32 v132, v1, v132
	v_add_f32_e32 v145, 0, v145
	v_fmac_f32_e32 v80, v6, v134
	v_fmac_f32_e32 v132, v0, v130
	v_mul_f32_e32 v130, v3, v133
	v_add_f32_e32 v136, v136, v145
	v_add_f32_e32 v80, v137, v80
	v_fmac_f32_e32 v130, v2, v131
	v_add_f32_e32 v80, v80, v136
	v_add_f32_e32 v130, v132, v130
	v_add_f32_e32 v80, v130, v80
	s_waitcnt lgkmcnt(0)
	s_nop 1
	v_add_f32_dpp v80, v80, v80 quad_perm:[1,0,3,2] row_mask:0xf bank_mask:0xf
	s_nop 1
	v_add_f32_dpp v80, v80, v80 quad_perm:[2,3,0,1] row_mask:0xf bank_mask:0xf
	s_nop 1
	v_add_f32_dpp v80, v80, v80 row_half_mirror row_mask:0xf bank_mask:0xf
	s_nop 1
	v_add_f32_dpp v80, v80, v80 row_mirror row_mask:0xf bank_mask:0xf
	s_nop 1
	v_readlane_b32 s100, v80, 16
	v_readlane_b32 s101, v80, 32
	s_nop 1
	v_add_f32_e32 v130, s100, v80
	v_readlane_b32 s100, v80, 48
	v_add_f32_e32 v130, s101, v130
	s_nop 1
	v_add_f32_e32 v80, s100, v130
	s_and_saveexec_b64 s[14:15], s[38:39]
	s_cbranch_execz .LBB0_66
	v_mov_b32_e32 v130, s28
	global_store_dword v130, v80, s[12:13] offset:4 sc1
.LBB0_66:
	s_or_b64 exec, exec, s[14:15]
	v_and_b32_e32 v134, 0xffff0000, v126
	v_and_b32_e32 v136, 0xffff0000, v127
	v_lshlrev_b32_e32 v131, 16, v126
	v_lshlrev_b32_e32 v133, 16, v127
	v_mul_f32_e32 v137, v77, v134
	v_mul_f32_e32 v143, v79, v136
	v_lshlrev_b32_e32 v132, 16, v128
	v_and_b32_e32 v135, 0xffff0000, v128
	v_lshlrev_b32_e32 v128, 16, v129
	v_and_b32_e32 v129, 0xffff0000, v129
	v_fmac_f32_e32 v137, v76, v131
	v_fmac_f32_e32 v143, v78, v133
	v_add_f32_e32 v137, v137, v143
	v_mul_f32_e32 v143, v73, v135
	v_mul_f32_e32 v145, v75, v129
	v_fmac_f32_e32 v143, v72, v132
	v_fmac_f32_e32 v145, v74, v128
	s_waitcnt lgkmcnt(0)
	v_and_b32_e32 v130, 0xffff0000, v122
	v_and_b32_e32 v127, 0xffff0000, v123
	v_add_f32_e32 v137, 0, v137
	v_add_f32_e32 v143, v143, v145
	v_lshlrev_b32_e32 v80, 16, v122
	v_lshlrev_b32_e32 v126, 16, v123
	v_add_f32_e32 v137, v143, v137
	v_mul_f32_e32 v143, v69, v130
	v_mul_f32_e32 v145, v71, v127
	v_fmac_f32_e32 v143, v68, v80
	v_fmac_f32_e32 v145, v70, v126
	v_lshlrev_b32_e32 v122, 16, v124
	v_and_b32_e32 v124, 0xffff0000, v124
	v_lshlrev_b32_e32 v123, 16, v125
	v_and_b32_e32 v125, 0xffff0000, v125
	v_add_f32_e32 v143, v143, v145
	v_add_f32_e32 v137, v143, v137
	v_mul_f32_e32 v143, v65, v124
	v_mul_f32_e32 v145, v67, v125
	v_fmac_f32_e32 v143, v64, v122
	v_fmac_f32_e32 v145, v66, v123
	v_add_f32_e32 v143, v143, v145
	v_add_f32_e32 v137, v143, v137
	s_waitcnt lgkmcnt(0)
	s_nop 1
	v_add_f32_dpp v137, v137, v137 quad_perm:[1,0,3,2] row_mask:0xf bank_mask:0xf
	s_nop 1
	v_add_f32_dpp v137, v137, v137 quad_perm:[2,3,0,1] row_mask:0xf bank_mask:0xf
	s_nop 1
	v_add_f32_dpp v137, v137, v137 row_half_mirror row_mask:0xf bank_mask:0xf
	s_nop 1
	v_add_f32_dpp v137, v137, v137 row_mirror row_mask:0xf bank_mask:0xf
	s_nop 1
	v_readlane_b32 s100, v137, 16
	v_readlane_b32 s101, v137, 32
	s_nop 1
	v_add_f32_e32 v143, s100, v137
	v_readlane_b32 s100, v137, 48
	v_add_f32_e32 v143, s101, v143
	s_nop 1
	v_add_f32_e32 v137, s100, v143
	s_and_saveexec_b64 s[14:15], s[38:39]
	s_cbranch_execz .LBB0_68
	v_mov_b32_e32 v143, s18
	global_store_dword v143, v137, s[12:13] offset:8 sc1
.LBB0_68:
	s_or_b64 exec, exec, s[14:15]
	v_mul_f32_e32 v137, v61, v134
	s_waitcnt lgkmcnt(0)
	v_mul_f32_e32 v143, v63, v136
	v_fmac_f32_e32 v137, v60, v131
	v_fmac_f32_e32 v143, v62, v133
	v_add_f32_e32 v137, v137, v143
	v_mul_f32_e32 v143, v57, v135
	v_mul_f32_e32 v145, v59, v129
	v_fmac_f32_e32 v143, v56, v132
	v_fmac_f32_e32 v145, v58, v128
	v_add_f32_e32 v137, 0, v137
	v_add_f32_e32 v143, v143, v145
	v_add_f32_e32 v137, v143, v137
	v_mul_f32_e32 v143, v49, v130
	v_mul_f32_e32 v145, v51, v127
	v_fmac_f32_e32 v143, v48, v80
	v_fmac_f32_e32 v145, v50, v126
	v_add_f32_e32 v143, v143, v145
	v_add_f32_e32 v137, v143, v137
	v_mul_f32_e32 v143, v53, v124
	v_mul_f32_e32 v145, v55, v125
	v_fmac_f32_e32 v143, v52, v122
	v_fmac_f32_e32 v145, v54, v123
	v_add_f32_e32 v143, v143, v145
	v_add_f32_e32 v137, v143, v137
	s_waitcnt lgkmcnt(0)
	s_nop 1
	v_add_f32_dpp v137, v137, v137 quad_perm:[1,0,3,2] row_mask:0xf bank_mask:0xf
	s_nop 1
	v_add_f32_dpp v137, v137, v137 quad_perm:[2,3,0,1] row_mask:0xf bank_mask:0xf
	s_nop 1
	v_add_f32_dpp v137, v137, v137 row_half_mirror row_mask:0xf bank_mask:0xf
	s_nop 1
	v_add_f32_dpp v137, v137, v137 row_mirror row_mask:0xf bank_mask:0xf
	s_nop 1
	v_readlane_b32 s100, v137, 16
	v_readlane_b32 s101, v137, 32
	s_nop 1
	v_add_f32_e32 v143, s100, v137
	v_readlane_b32 s100, v137, 48
	v_add_f32_e32 v143, s101, v143
	s_nop 1
	v_add_f32_e32 v137, s100, v143
	s_and_saveexec_b64 s[14:15], s[38:39]
	s_cbranch_execz .LBB0_70
	v_mov_b32_e32 v143, s19
	global_store_dword v143, v137, s[12:13] offset:8 sc1
.LBB0_70:
	s_or_b64 exec, exec, s[14:15]
	v_mul_f32_e32 v137, v45, v134
	s_waitcnt lgkmcnt(0)
	v_mul_f32_e32 v143, v47, v136
	v_fmac_f32_e32 v137, v44, v131
	v_fmac_f32_e32 v143, v46, v133
	v_add_f32_e32 v137, v137, v143
	v_mul_f32_e32 v143, v41, v135
	v_mul_f32_e32 v145, v43, v129
	v_fmac_f32_e32 v143, v40, v132
	v_fmac_f32_e32 v145, v42, v128
	v_add_f32_e32 v137, 0, v137
	v_add_f32_e32 v143, v143, v145
	v_add_f32_e32 v137, v143, v137
	v_mul_f32_e32 v143, v33, v130
	v_mul_f32_e32 v145, v35, v127
	v_fmac_f32_e32 v143, v32, v80
	v_fmac_f32_e32 v145, v34, v126
	v_add_f32_e32 v143, v143, v145
	v_add_f32_e32 v137, v143, v137
	v_mul_f32_e32 v143, v37, v124
	v_mul_f32_e32 v145, v39, v125
	v_fmac_f32_e32 v143, v36, v122
	v_fmac_f32_e32 v145, v38, v123
	v_add_f32_e32 v143, v143, v145
	v_add_f32_e32 v137, v143, v137
	s_waitcnt lgkmcnt(0)
	s_nop 1
	v_add_f32_dpp v137, v137, v137 quad_perm:[1,0,3,2] row_mask:0xf bank_mask:0xf
	s_nop 1
	v_add_f32_dpp v137, v137, v137 quad_perm:[2,3,0,1] row_mask:0xf bank_mask:0xf
	s_nop 1
	v_add_f32_dpp v137, v137, v137 row_half_mirror row_mask:0xf bank_mask:0xf
	s_nop 1
	v_add_f32_dpp v137, v137, v137 row_mirror row_mask:0xf bank_mask:0xf
	s_nop 1
	v_readlane_b32 s100, v137, 16
	v_readlane_b32 s101, v137, 32
	s_nop 1
	v_add_f32_e32 v143, s100, v137
	v_readlane_b32 s100, v137, 48
	v_add_f32_e32 v143, s101, v143
	s_nop 1
	v_add_f32_e32 v137, s100, v143
	s_and_saveexec_b64 s[14:15], s[38:39]
	s_cbranch_execz .LBB0_72
	v_mov_b32_e32 v143, s26
	global_store_dword v143, v137, s[12:13] offset:8 sc1
.LBB0_72:
	s_or_b64 exec, exec, s[14:15]
	v_mul_f32_e32 v137, v29, v134
	s_waitcnt lgkmcnt(0)
	v_mul_f32_e32 v143, v31, v136
	v_fmac_f32_e32 v137, v28, v131
	v_fmac_f32_e32 v143, v30, v133
	v_add_f32_e32 v137, v137, v143
	v_mul_f32_e32 v143, v25, v135
	v_mul_f32_e32 v145, v27, v129
	v_fmac_f32_e32 v143, v24, v132
	v_fmac_f32_e32 v145, v26, v128
	v_add_f32_e32 v137, 0, v137
	v_add_f32_e32 v143, v143, v145
	v_add_f32_e32 v137, v143, v137
	v_mul_f32_e32 v143, v21, v130
	v_mul_f32_e32 v145, v23, v127
	v_fmac_f32_e32 v143, v20, v80
	v_fmac_f32_e32 v145, v22, v126
	v_add_f32_e32 v143, v143, v145
	v_add_f32_e32 v137, v143, v137
	v_mul_f32_e32 v143, v17, v124
	v_mul_f32_e32 v145, v19, v125
	v_fmac_f32_e32 v143, v16, v122
	v_fmac_f32_e32 v145, v18, v123
	v_add_f32_e32 v143, v143, v145
	v_add_f32_e32 v137, v143, v137
	s_waitcnt lgkmcnt(0)
	s_nop 1
	v_add_f32_dpp v137, v137, v137 quad_perm:[1,0,3,2] row_mask:0xf bank_mask:0xf
	s_nop 1
	v_add_f32_dpp v137, v137, v137 quad_perm:[2,3,0,1] row_mask:0xf bank_mask:0xf
	s_nop 1
	v_add_f32_dpp v137, v137, v137 row_half_mirror row_mask:0xf bank_mask:0xf
	s_nop 1
	v_add_f32_dpp v137, v137, v137 row_mirror row_mask:0xf bank_mask:0xf
	s_nop 1
	v_readlane_b32 s100, v137, 16
	v_readlane_b32 s101, v137, 32
	s_nop 1
	v_add_f32_e32 v143, s100, v137
	v_readlane_b32 s100, v137, 48
	v_add_f32_e32 v143, s101, v143
	s_nop 1
	v_add_f32_e32 v137, s100, v143
	s_and_saveexec_b64 s[14:15], s[38:39]
	s_cbranch_execz .LBB0_74
	v_mov_b32_e32 v143, s27
	global_store_dword v143, v137, s[12:13] offset:8 sc1
.LBB0_74:
	s_or_b64 exec, exec, s[14:15]
	v_mul_f32_e32 v134, v13, v134
	v_fmac_f32_e32 v134, v12, v131
	v_mul_f32_e32 v131, v15, v136
	v_fmac_f32_e32 v131, v14, v133
	v_mul_f32_e32 v133, v9, v135
	v_mul_f32_e32 v129, v11, v129
	v_fmac_f32_e32 v133, v8, v132
	v_fmac_f32_e32 v129, v10, v128
	v_add_f32_e32 v128, v133, v129
	v_mul_f32_e32 v129, v5, v130
	v_add_f32_e32 v131, v134, v131
	v_fmac_f32_e32 v129, v4, v80
	v_mul_f32_e32 v80, v7, v127
	v_mul_f32_e32 v124, v1, v124
	v_add_f32_e32 v131, 0, v131
	v_fmac_f32_e32 v80, v6, v126
	v_fmac_f32_e32 v124, v0, v122
	v_mul_f32_e32 v122, v3, v125
	v_add_f32_e32 v128, v128, v131
	v_add_f32_e32 v80, v129, v80
	v_fmac_f32_e32 v122, v2, v123
	v_add_f32_e32 v80, v80, v128
	v_add_f32_e32 v122, v124, v122
	v_add_f32_e32 v80, v122, v80
	s_waitcnt lgkmcnt(0)
	s_nop 1
	v_add_f32_dpp v80, v80, v80 quad_perm:[1,0,3,2] row_mask:0xf bank_mask:0xf
	s_nop 1
	v_add_f32_dpp v80, v80, v80 quad_perm:[2,3,0,1] row_mask:0xf bank_mask:0xf
	s_nop 1
	v_add_f32_dpp v80, v80, v80 row_half_mirror row_mask:0xf bank_mask:0xf
	s_nop 1
	v_add_f32_dpp v80, v80, v80 row_mirror row_mask:0xf bank_mask:0xf
	s_nop 1
	v_readlane_b32 s100, v80, 16
	v_readlane_b32 s101, v80, 32
	s_nop 1
	v_add_f32_e32 v122, s100, v80
	v_readlane_b32 s100, v80, 48
	v_add_f32_e32 v122, s101, v122
	s_nop 1
	v_add_f32_e32 v80, s100, v122
	s_and_saveexec_b64 s[14:15], s[38:39]
	s_cbranch_execz .LBB0_76
	v_mov_b32_e32 v122, s28
	global_store_dword v122, v80, s[12:13] offset:8 sc1
.LBB0_76:
	s_or_b64 exec, exec, s[14:15]
	v_and_b32_e32 v126, 0xffff0000, v118
	v_and_b32_e32 v128, 0xffff0000, v119
	v_lshlrev_b32_e32 v123, 16, v118
	v_lshlrev_b32_e32 v125, 16, v119
	v_mul_f32_e32 v129, v77, v126
	v_mul_f32_e32 v130, v79, v128
	v_lshlrev_b32_e32 v124, 16, v120
	v_and_b32_e32 v127, 0xffff0000, v120
	v_lshlrev_b32_e32 v120, 16, v121
	v_and_b32_e32 v121, 0xffff0000, v121
	v_fmac_f32_e32 v129, v76, v123
	v_fmac_f32_e32 v130, v78, v125
	v_add_f32_e32 v129, v129, v130
	v_mul_f32_e32 v130, v73, v127
	v_mul_f32_e32 v131, v75, v121
	v_fmac_f32_e32 v130, v72, v124
	v_fmac_f32_e32 v131, v74, v120
	s_waitcnt lgkmcnt(0)
	v_and_b32_e32 v122, 0xffff0000, v114
	v_and_b32_e32 v119, 0xffff0000, v115
	v_add_f32_e32 v129, 0, v129
	v_add_f32_e32 v130, v130, v131
	v_lshlrev_b32_e32 v80, 16, v114
	v_lshlrev_b32_e32 v118, 16, v115
	v_add_f32_e32 v129, v130, v129
	v_mul_f32_e32 v130, v69, v122
	v_mul_f32_e32 v131, v71, v119
	v_fmac_f32_e32 v130, v68, v80
	v_fmac_f32_e32 v131, v70, v118
	v_lshlrev_b32_e32 v114, 16, v116
	v_and_b32_e32 v116, 0xffff0000, v116
	v_lshlrev_b32_e32 v115, 16, v117
	v_and_b32_e32 v117, 0xffff0000, v117
	v_add_f32_e32 v130, v130, v131
	v_add_f32_e32 v129, v130, v129
	v_mul_f32_e32 v130, v65, v116
	v_mul_f32_e32 v131, v67, v117
	v_fmac_f32_e32 v130, v64, v114
	v_fmac_f32_e32 v131, v66, v115
	v_add_f32_e32 v130, v130, v131
	v_add_f32_e32 v129, v130, v129
	s_waitcnt lgkmcnt(0)
	s_nop 1
	v_add_f32_dpp v129, v129, v129 quad_perm:[1,0,3,2] row_mask:0xf bank_mask:0xf
	s_nop 1
	v_add_f32_dpp v129, v129, v129 quad_perm:[2,3,0,1] row_mask:0xf bank_mask:0xf
	s_nop 1
	v_add_f32_dpp v129, v129, v129 row_half_mirror row_mask:0xf bank_mask:0xf
	s_nop 1
	v_add_f32_dpp v129, v129, v129 row_mirror row_mask:0xf bank_mask:0xf
	s_nop 1
	v_readlane_b32 s100, v129, 16
	v_readlane_b32 s101, v129, 32
	s_nop 1
	v_add_f32_e32 v130, s100, v129
	v_readlane_b32 s100, v129, 48
	v_add_f32_e32 v130, s101, v130
	s_nop 1
	v_add_f32_e32 v129, s100, v130
	s_and_saveexec_b64 s[14:15], s[38:39]
	s_cbranch_execz .LBB0_78
	v_mov_b32_e32 v130, s18
	global_store_dword v130, v129, s[12:13] offset:12 sc1
.LBB0_78:
	s_or_b64 exec, exec, s[14:15]
	v_mul_f32_e32 v129, v61, v126
	s_waitcnt lgkmcnt(0)
	v_mul_f32_e32 v130, v63, v128
	v_fmac_f32_e32 v129, v60, v123
	v_fmac_f32_e32 v130, v62, v125
	v_add_f32_e32 v129, v129, v130
	v_mul_f32_e32 v130, v57, v127
	v_mul_f32_e32 v131, v59, v121
	v_fmac_f32_e32 v130, v56, v124
	v_fmac_f32_e32 v131, v58, v120
	v_add_f32_e32 v129, 0, v129
	v_add_f32_e32 v130, v130, v131
	v_add_f32_e32 v129, v130, v129
	v_mul_f32_e32 v130, v49, v122
	v_mul_f32_e32 v131, v51, v119
	v_fmac_f32_e32 v130, v48, v80
	v_fmac_f32_e32 v131, v50, v118
	v_add_f32_e32 v130, v130, v131
	v_add_f32_e32 v129, v130, v129
	v_mul_f32_e32 v130, v53, v116
	v_mul_f32_e32 v131, v55, v117
	v_fmac_f32_e32 v130, v52, v114
	v_fmac_f32_e32 v131, v54, v115
	v_add_f32_e32 v130, v130, v131
	v_add_f32_e32 v129, v130, v129
	s_waitcnt lgkmcnt(0)
	s_nop 1
	v_add_f32_dpp v129, v129, v129 quad_perm:[1,0,3,2] row_mask:0xf bank_mask:0xf
	s_nop 1
	v_add_f32_dpp v129, v129, v129 quad_perm:[2,3,0,1] row_mask:0xf bank_mask:0xf
	s_nop 1
	v_add_f32_dpp v129, v129, v129 row_half_mirror row_mask:0xf bank_mask:0xf
	s_nop 1
	v_add_f32_dpp v129, v129, v129 row_mirror row_mask:0xf bank_mask:0xf
	s_nop 1
	v_readlane_b32 s100, v129, 16
	v_readlane_b32 s101, v129, 32
	s_nop 1
	v_add_f32_e32 v130, s100, v129
	v_readlane_b32 s100, v129, 48
	v_add_f32_e32 v130, s101, v130
	s_nop 1
	v_add_f32_e32 v129, s100, v130
	s_and_saveexec_b64 s[14:15], s[38:39]
	s_cbranch_execz .LBB0_80
	v_mov_b32_e32 v130, s19
	global_store_dword v130, v129, s[12:13] offset:12 sc1
.LBB0_80:
	s_or_b64 exec, exec, s[14:15]
	v_mul_f32_e32 v129, v45, v126
	s_waitcnt lgkmcnt(0)
	v_mul_f32_e32 v130, v47, v128
	v_fmac_f32_e32 v129, v44, v123
	v_fmac_f32_e32 v130, v46, v125
	v_add_f32_e32 v129, v129, v130
	v_mul_f32_e32 v130, v41, v127
	v_mul_f32_e32 v131, v43, v121
	v_fmac_f32_e32 v130, v40, v124
	v_fmac_f32_e32 v131, v42, v120
	v_add_f32_e32 v129, 0, v129
	v_add_f32_e32 v130, v130, v131
	v_add_f32_e32 v129, v130, v129
	v_mul_f32_e32 v130, v33, v122
	v_mul_f32_e32 v131, v35, v119
	v_fmac_f32_e32 v130, v32, v80
	v_fmac_f32_e32 v131, v34, v118
	v_add_f32_e32 v130, v130, v131
	v_add_f32_e32 v129, v130, v129
	v_mul_f32_e32 v130, v37, v116
	v_mul_f32_e32 v131, v39, v117
	v_fmac_f32_e32 v130, v36, v114
	v_fmac_f32_e32 v131, v38, v115
	v_add_f32_e32 v130, v130, v131
	v_add_f32_e32 v129, v130, v129
	s_waitcnt lgkmcnt(0)
	s_nop 1
	v_add_f32_dpp v129, v129, v129 quad_perm:[1,0,3,2] row_mask:0xf bank_mask:0xf
	s_nop 1
	v_add_f32_dpp v129, v129, v129 quad_perm:[2,3,0,1] row_mask:0xf bank_mask:0xf
	s_nop 1
	v_add_f32_dpp v129, v129, v129 row_half_mirror row_mask:0xf bank_mask:0xf
	s_nop 1
	v_add_f32_dpp v129, v129, v129 row_mirror row_mask:0xf bank_mask:0xf
	s_nop 1
	v_readlane_b32 s100, v129, 16
	v_readlane_b32 s101, v129, 32
	s_nop 1
	v_add_f32_e32 v130, s100, v129
	v_readlane_b32 s100, v129, 48
	v_add_f32_e32 v130, s101, v130
	s_nop 1
	v_add_f32_e32 v129, s100, v130
	s_and_saveexec_b64 s[14:15], s[38:39]
	s_cbranch_execz .LBB0_82
	v_mov_b32_e32 v130, s26
	global_store_dword v130, v129, s[12:13] offset:12 sc1
.LBB0_82:
	s_or_b64 exec, exec, s[14:15]
	v_mul_f32_e32 v129, v29, v126
	s_waitcnt lgkmcnt(0)
	v_mul_f32_e32 v130, v31, v128
	v_fmac_f32_e32 v129, v28, v123
	v_fmac_f32_e32 v130, v30, v125
	v_add_f32_e32 v129, v129, v130
	v_mul_f32_e32 v130, v25, v127
	v_mul_f32_e32 v131, v27, v121
	v_fmac_f32_e32 v130, v24, v124
	v_fmac_f32_e32 v131, v26, v120
	v_add_f32_e32 v129, 0, v129
	v_add_f32_e32 v130, v130, v131
	v_add_f32_e32 v129, v130, v129
	v_mul_f32_e32 v130, v21, v122
	v_mul_f32_e32 v131, v23, v119
	v_fmac_f32_e32 v130, v20, v80
	v_fmac_f32_e32 v131, v22, v118
	v_add_f32_e32 v130, v130, v131
	v_add_f32_e32 v129, v130, v129
	v_mul_f32_e32 v130, v17, v116
	v_mul_f32_e32 v131, v19, v117
	v_fmac_f32_e32 v130, v16, v114
	v_fmac_f32_e32 v131, v18, v115
	v_add_f32_e32 v130, v130, v131
	v_add_f32_e32 v129, v130, v129
	s_waitcnt lgkmcnt(0)
	s_nop 1
	v_add_f32_dpp v129, v129, v129 quad_perm:[1,0,3,2] row_mask:0xf bank_mask:0xf
	s_nop 1
	v_add_f32_dpp v129, v129, v129 quad_perm:[2,3,0,1] row_mask:0xf bank_mask:0xf
	s_nop 1
	v_add_f32_dpp v129, v129, v129 row_half_mirror row_mask:0xf bank_mask:0xf
	s_nop 1
	v_add_f32_dpp v129, v129, v129 row_mirror row_mask:0xf bank_mask:0xf
	s_nop 1
	v_readlane_b32 s100, v129, 16
	v_readlane_b32 s101, v129, 32
	s_nop 1
	v_add_f32_e32 v130, s100, v129
	v_readlane_b32 s100, v129, 48
	v_add_f32_e32 v130, s101, v130
	s_nop 1
	v_add_f32_e32 v129, s100, v130
	s_and_saveexec_b64 s[14:15], s[38:39]
	s_cbranch_execz .LBB0_84
	v_mov_b32_e32 v130, s27
	global_store_dword v130, v129, s[12:13] offset:12 sc1
.LBB0_84:
	s_or_b64 exec, exec, s[14:15]
	v_mul_f32_e32 v126, v13, v126
	v_fmac_f32_e32 v126, v12, v123
	v_mul_f32_e32 v123, v15, v128
	v_fmac_f32_e32 v123, v14, v125
	v_mul_f32_e32 v125, v9, v127
	v_mul_f32_e32 v121, v11, v121
	v_fmac_f32_e32 v125, v8, v124
	v_fmac_f32_e32 v121, v10, v120
	v_add_f32_e32 v120, v125, v121
	v_mul_f32_e32 v121, v5, v122
	v_add_f32_e32 v123, v126, v123
	v_fmac_f32_e32 v121, v4, v80
	v_mul_f32_e32 v80, v7, v119
	v_mul_f32_e32 v116, v1, v116
	v_add_f32_e32 v123, 0, v123
	v_fmac_f32_e32 v80, v6, v118
	v_fmac_f32_e32 v116, v0, v114
	v_mul_f32_e32 v114, v3, v117
	v_add_f32_e32 v120, v120, v123
	v_add_f32_e32 v80, v121, v80
	v_fmac_f32_e32 v114, v2, v115
	v_add_f32_e32 v80, v80, v120
	v_add_f32_e32 v114, v116, v114
	v_add_f32_e32 v80, v114, v80
	s_waitcnt lgkmcnt(0)
	s_nop 1
	v_add_f32_dpp v80, v80, v80 quad_perm:[1,0,3,2] row_mask:0xf bank_mask:0xf
	s_nop 1
	v_add_f32_dpp v80, v80, v80 quad_perm:[2,3,0,1] row_mask:0xf bank_mask:0xf
	s_nop 1
	v_add_f32_dpp v80, v80, v80 row_half_mirror row_mask:0xf bank_mask:0xf
	s_nop 1
	v_add_f32_dpp v80, v80, v80 row_mirror row_mask:0xf bank_mask:0xf
	s_nop 1
	v_readlane_b32 s100, v80, 16
	v_readlane_b32 s101, v80, 32
	s_nop 1
	v_add_f32_e32 v114, s100, v80
	v_readlane_b32 s100, v80, 48
	v_add_f32_e32 v114, s101, v114
	s_nop 1
	v_add_f32_e32 v80, s100, v114
	s_and_saveexec_b64 s[14:15], s[38:39]
	s_cbranch_execz .LBB0_86
	v_mov_b32_e32 v114, s28
	global_store_dword v114, v80, s[12:13] offset:12 sc1
.LBB0_86:
	s_or_b64 exec, exec, s[14:15]
	v_and_b32_e32 v118, 0xffff0000, v110
	v_and_b32_e32 v120, 0xffff0000, v111
	v_lshlrev_b32_e32 v115, 16, v110
	v_lshlrev_b32_e32 v117, 16, v111
	v_mul_f32_e32 v121, v77, v118
	v_mul_f32_e32 v122, v79, v120
	v_lshlrev_b32_e32 v116, 16, v112
	v_and_b32_e32 v119, 0xffff0000, v112
	v_lshlrev_b32_e32 v112, 16, v113
	v_and_b32_e32 v113, 0xffff0000, v113
	v_fmac_f32_e32 v121, v76, v115
	v_fmac_f32_e32 v122, v78, v117
	v_add_f32_e32 v121, v121, v122
	v_mul_f32_e32 v122, v73, v119
	v_mul_f32_e32 v123, v75, v113
	v_fmac_f32_e32 v122, v72, v116
	v_fmac_f32_e32 v123, v74, v112
	s_waitcnt lgkmcnt(0)
	v_and_b32_e32 v114, 0xffff0000, v106
	v_and_b32_e32 v111, 0xffff0000, v107
	v_add_f32_e32 v121, 0, v121
	v_add_f32_e32 v122, v122, v123
	v_lshlrev_b32_e32 v80, 16, v106
	v_lshlrev_b32_e32 v110, 16, v107
	v_add_f32_e32 v121, v122, v121
	v_mul_f32_e32 v122, v69, v114
	v_mul_f32_e32 v123, v71, v111
	v_fmac_f32_e32 v122, v68, v80
	v_fmac_f32_e32 v123, v70, v110
	v_lshlrev_b32_e32 v106, 16, v108
	v_and_b32_e32 v108, 0xffff0000, v108
	v_lshlrev_b32_e32 v107, 16, v109
	v_and_b32_e32 v109, 0xffff0000, v109
	v_add_f32_e32 v122, v122, v123
	v_add_f32_e32 v121, v122, v121
	v_mul_f32_e32 v122, v65, v108
	v_mul_f32_e32 v123, v67, v109
	v_fmac_f32_e32 v122, v64, v106
	v_fmac_f32_e32 v123, v66, v107
	v_add_f32_e32 v122, v122, v123
	v_add_f32_e32 v121, v122, v121
	s_waitcnt lgkmcnt(0)
	s_nop 1
	v_add_f32_dpp v121, v121, v121 quad_perm:[1,0,3,2] row_mask:0xf bank_mask:0xf
	s_nop 1
	v_add_f32_dpp v121, v121, v121 quad_perm:[2,3,0,1] row_mask:0xf bank_mask:0xf
	s_nop 1
	v_add_f32_dpp v121, v121, v121 row_half_mirror row_mask:0xf bank_mask:0xf
	s_nop 1
	v_add_f32_dpp v121, v121, v121 row_mirror row_mask:0xf bank_mask:0xf
	s_nop 1
	v_readlane_b32 s100, v121, 16
	v_readlane_b32 s101, v121, 32
	s_nop 1
	v_add_f32_e32 v122, s100, v121
	v_readlane_b32 s100, v121, 48
	v_add_f32_e32 v122, s101, v122
	s_nop 1
	v_add_f32_e32 v121, s100, v122
	s_and_saveexec_b64 s[14:15], s[38:39]
	s_cbranch_execz .LBB0_88
	v_mov_b32_e32 v122, s18
	global_store_dword v122, v121, s[12:13] offset:16 sc1
.LBB0_88:
	s_or_b64 exec, exec, s[14:15]
	v_mul_f32_e32 v121, v61, v118
	s_waitcnt lgkmcnt(0)
	v_mul_f32_e32 v122, v63, v120
	v_fmac_f32_e32 v121, v60, v115
	v_fmac_f32_e32 v122, v62, v117
	v_add_f32_e32 v121, v121, v122
	v_mul_f32_e32 v122, v57, v119
	v_mul_f32_e32 v123, v59, v113
	v_fmac_f32_e32 v122, v56, v116
	v_fmac_f32_e32 v123, v58, v112
	v_add_f32_e32 v121, 0, v121
	v_add_f32_e32 v122, v122, v123
	v_add_f32_e32 v121, v122, v121
	v_mul_f32_e32 v122, v49, v114
	v_mul_f32_e32 v123, v51, v111
	v_fmac_f32_e32 v122, v48, v80
	v_fmac_f32_e32 v123, v50, v110
	v_add_f32_e32 v122, v122, v123
	v_add_f32_e32 v121, v122, v121
	v_mul_f32_e32 v122, v53, v108
	v_mul_f32_e32 v123, v55, v109
	v_fmac_f32_e32 v122, v52, v106
	v_fmac_f32_e32 v123, v54, v107
	v_add_f32_e32 v122, v122, v123
	v_add_f32_e32 v121, v122, v121
	s_waitcnt lgkmcnt(0)
	s_nop 1
	v_add_f32_dpp v121, v121, v121 quad_perm:[1,0,3,2] row_mask:0xf bank_mask:0xf
	s_nop 1
	v_add_f32_dpp v121, v121, v121 quad_perm:[2,3,0,1] row_mask:0xf bank_mask:0xf
	s_nop 1
	v_add_f32_dpp v121, v121, v121 row_half_mirror row_mask:0xf bank_mask:0xf
	s_nop 1
	v_add_f32_dpp v121, v121, v121 row_mirror row_mask:0xf bank_mask:0xf
	s_nop 1
	v_readlane_b32 s100, v121, 16
	v_readlane_b32 s101, v121, 32
	s_nop 1
	v_add_f32_e32 v122, s100, v121
	v_readlane_b32 s100, v121, 48
	v_add_f32_e32 v122, s101, v122
	s_nop 1
	v_add_f32_e32 v121, s100, v122
	s_and_saveexec_b64 s[14:15], s[38:39]
	s_cbranch_execz .LBB0_90
	v_mov_b32_e32 v122, s19
	global_store_dword v122, v121, s[12:13] offset:16 sc1
.LBB0_90:
	s_or_b64 exec, exec, s[14:15]
	v_mul_f32_e32 v121, v45, v118
	s_waitcnt lgkmcnt(0)
	v_mul_f32_e32 v122, v47, v120
	v_fmac_f32_e32 v121, v44, v115
	v_fmac_f32_e32 v122, v46, v117
	v_add_f32_e32 v121, v121, v122
	v_mul_f32_e32 v122, v41, v119
	v_mul_f32_e32 v123, v43, v113
	v_fmac_f32_e32 v122, v40, v116
	v_fmac_f32_e32 v123, v42, v112
	v_add_f32_e32 v121, 0, v121
	v_add_f32_e32 v122, v122, v123
	v_add_f32_e32 v121, v122, v121
	v_mul_f32_e32 v122, v33, v114
	v_mul_f32_e32 v123, v35, v111
	v_fmac_f32_e32 v122, v32, v80
	v_fmac_f32_e32 v123, v34, v110
	v_add_f32_e32 v122, v122, v123
	v_add_f32_e32 v121, v122, v121
	v_mul_f32_e32 v122, v37, v108
	v_mul_f32_e32 v123, v39, v109
	v_fmac_f32_e32 v122, v36, v106
	v_fmac_f32_e32 v123, v38, v107
	v_add_f32_e32 v122, v122, v123
	v_add_f32_e32 v121, v122, v121
	s_waitcnt lgkmcnt(0)
	s_nop 1
	v_add_f32_dpp v121, v121, v121 quad_perm:[1,0,3,2] row_mask:0xf bank_mask:0xf
	s_nop 1
	v_add_f32_dpp v121, v121, v121 quad_perm:[2,3,0,1] row_mask:0xf bank_mask:0xf
	s_nop 1
	v_add_f32_dpp v121, v121, v121 row_half_mirror row_mask:0xf bank_mask:0xf
	s_nop 1
	v_add_f32_dpp v121, v121, v121 row_mirror row_mask:0xf bank_mask:0xf
	s_nop 1
	v_readlane_b32 s100, v121, 16
	v_readlane_b32 s101, v121, 32
	s_nop 1
	v_add_f32_e32 v122, s100, v121
	v_readlane_b32 s100, v121, 48
	v_add_f32_e32 v122, s101, v122
	s_nop 1
	v_add_f32_e32 v121, s100, v122
	s_and_saveexec_b64 s[14:15], s[38:39]
	s_cbranch_execz .LBB0_92
	v_mov_b32_e32 v122, s26
	global_store_dword v122, v121, s[12:13] offset:16 sc1
.LBB0_92:
	s_or_b64 exec, exec, s[14:15]
	v_mul_f32_e32 v121, v29, v118
	s_waitcnt lgkmcnt(0)
	v_mul_f32_e32 v122, v31, v120
	v_fmac_f32_e32 v121, v28, v115
	v_fmac_f32_e32 v122, v30, v117
	v_add_f32_e32 v121, v121, v122
	v_mul_f32_e32 v122, v25, v119
	v_mul_f32_e32 v123, v27, v113
	v_fmac_f32_e32 v122, v24, v116
	v_fmac_f32_e32 v123, v26, v112
	v_add_f32_e32 v121, 0, v121
	v_add_f32_e32 v122, v122, v123
	v_add_f32_e32 v121, v122, v121
	v_mul_f32_e32 v122, v21, v114
	v_mul_f32_e32 v123, v23, v111
	v_fmac_f32_e32 v122, v20, v80
	v_fmac_f32_e32 v123, v22, v110
	v_add_f32_e32 v122, v122, v123
	v_add_f32_e32 v121, v122, v121
	v_mul_f32_e32 v122, v17, v108
	v_mul_f32_e32 v123, v19, v109
	v_fmac_f32_e32 v122, v16, v106
	v_fmac_f32_e32 v123, v18, v107
	v_add_f32_e32 v122, v122, v123
	v_add_f32_e32 v121, v122, v121
	s_waitcnt lgkmcnt(0)
	s_nop 1
	v_add_f32_dpp v121, v121, v121 quad_perm:[1,0,3,2] row_mask:0xf bank_mask:0xf
	s_nop 1
	v_add_f32_dpp v121, v121, v121 quad_perm:[2,3,0,1] row_mask:0xf bank_mask:0xf
	s_nop 1
	v_add_f32_dpp v121, v121, v121 row_half_mirror row_mask:0xf bank_mask:0xf
	s_nop 1
	v_add_f32_dpp v121, v121, v121 row_mirror row_mask:0xf bank_mask:0xf
	s_nop 1
	v_readlane_b32 s100, v121, 16
	v_readlane_b32 s101, v121, 32
	s_nop 1
	v_add_f32_e32 v122, s100, v121
	v_readlane_b32 s100, v121, 48
	v_add_f32_e32 v122, s101, v122
	s_nop 1
	v_add_f32_e32 v121, s100, v122
	s_and_saveexec_b64 s[14:15], s[38:39]
	s_cbranch_execz .LBB0_94
	v_mov_b32_e32 v122, s27
	global_store_dword v122, v121, s[12:13] offset:16 sc1
.LBB0_94:
	s_or_b64 exec, exec, s[14:15]
	v_mul_f32_e32 v118, v13, v118
	v_fmac_f32_e32 v118, v12, v115
	v_mul_f32_e32 v115, v15, v120
	v_fmac_f32_e32 v115, v14, v117
	v_mul_f32_e32 v117, v9, v119
	v_mul_f32_e32 v113, v11, v113
	v_fmac_f32_e32 v117, v8, v116
	v_fmac_f32_e32 v113, v10, v112
	v_add_f32_e32 v112, v117, v113
	v_mul_f32_e32 v113, v5, v114
	v_add_f32_e32 v115, v118, v115
	v_fmac_f32_e32 v113, v4, v80
	v_mul_f32_e32 v80, v7, v111
	v_mul_f32_e32 v108, v1, v108
	v_add_f32_e32 v115, 0, v115
	v_fmac_f32_e32 v80, v6, v110
	v_fmac_f32_e32 v108, v0, v106
	v_mul_f32_e32 v106, v3, v109
	v_add_f32_e32 v112, v112, v115
	v_add_f32_e32 v80, v113, v80
	v_fmac_f32_e32 v106, v2, v107
	v_add_f32_e32 v80, v80, v112
	v_add_f32_e32 v106, v108, v106
	v_add_f32_e32 v80, v106, v80
	s_waitcnt lgkmcnt(0)
	s_nop 1
	v_add_f32_dpp v80, v80, v80 quad_perm:[1,0,3,2] row_mask:0xf bank_mask:0xf
	s_nop 1
	v_add_f32_dpp v80, v80, v80 quad_perm:[2,3,0,1] row_mask:0xf bank_mask:0xf
	s_nop 1
	v_add_f32_dpp v80, v80, v80 row_half_mirror row_mask:0xf bank_mask:0xf
	s_nop 1
	v_add_f32_dpp v80, v80, v80 row_mirror row_mask:0xf bank_mask:0xf
	s_nop 1
	v_readlane_b32 s100, v80, 16
	v_readlane_b32 s101, v80, 32
	s_nop 1
	v_add_f32_e32 v106, s100, v80
	v_readlane_b32 s100, v80, 48
	v_add_f32_e32 v106, s101, v106
	s_nop 1
	v_add_f32_e32 v80, s100, v106
	s_and_saveexec_b64 s[14:15], s[38:39]
	s_cbranch_execz .LBB0_96
	v_mov_b32_e32 v106, s28
	global_store_dword v106, v80, s[12:13] offset:16 sc1
.LBB0_96:
	s_or_b64 exec, exec, s[14:15]
	v_and_b32_e32 v110, 0xffff0000, v102
	v_and_b32_e32 v112, 0xffff0000, v103
	v_lshlrev_b32_e32 v107, 16, v102
	v_lshlrev_b32_e32 v109, 16, v103
	v_mul_f32_e32 v113, v77, v110
	v_mul_f32_e32 v114, v79, v112
	v_lshlrev_b32_e32 v108, 16, v104
	v_and_b32_e32 v111, 0xffff0000, v104
	v_lshlrev_b32_e32 v104, 16, v105
	v_and_b32_e32 v105, 0xffff0000, v105
	v_fmac_f32_e32 v113, v76, v107
	v_fmac_f32_e32 v114, v78, v109
	v_add_f32_e32 v113, v113, v114
	v_mul_f32_e32 v114, v73, v111
	v_mul_f32_e32 v115, v75, v105
	v_fmac_f32_e32 v114, v72, v108
	v_fmac_f32_e32 v115, v74, v104
	s_waitcnt lgkmcnt(0)
	v_and_b32_e32 v106, 0xffff0000, v98
	v_and_b32_e32 v103, 0xffff0000, v99
	v_add_f32_e32 v113, 0, v113
	v_add_f32_e32 v114, v114, v115
	v_lshlrev_b32_e32 v80, 16, v98
	v_lshlrev_b32_e32 v102, 16, v99
	v_add_f32_e32 v113, v114, v113
	v_mul_f32_e32 v114, v69, v106
	v_mul_f32_e32 v115, v71, v103
	v_fmac_f32_e32 v114, v68, v80
	v_fmac_f32_e32 v115, v70, v102
	v_lshlrev_b32_e32 v98, 16, v100
	v_and_b32_e32 v100, 0xffff0000, v100
	v_lshlrev_b32_e32 v99, 16, v101
	v_and_b32_e32 v101, 0xffff0000, v101
	v_add_f32_e32 v114, v114, v115
	v_add_f32_e32 v113, v114, v113
	v_mul_f32_e32 v114, v65, v100
	v_mul_f32_e32 v115, v67, v101
	v_fmac_f32_e32 v114, v64, v98
	v_fmac_f32_e32 v115, v66, v99
	v_add_f32_e32 v114, v114, v115
	v_add_f32_e32 v113, v114, v113
	s_waitcnt lgkmcnt(0)
	s_nop 1
	v_add_f32_dpp v113, v113, v113 quad_perm:[1,0,3,2] row_mask:0xf bank_mask:0xf
	s_nop 1
	v_add_f32_dpp v113, v113, v113 quad_perm:[2,3,0,1] row_mask:0xf bank_mask:0xf
	s_nop 1
	v_add_f32_dpp v113, v113, v113 row_half_mirror row_mask:0xf bank_mask:0xf
	s_nop 1
	v_add_f32_dpp v113, v113, v113 row_mirror row_mask:0xf bank_mask:0xf
	s_nop 1
	v_readlane_b32 s100, v113, 16
	v_readlane_b32 s101, v113, 32
	s_nop 1
	v_add_f32_e32 v114, s100, v113
	v_readlane_b32 s100, v113, 48
	v_add_f32_e32 v114, s101, v114
	s_nop 1
	v_add_f32_e32 v113, s100, v114
	s_and_saveexec_b64 s[14:15], s[38:39]
	s_cbranch_execz .LBB0_98
	v_mov_b32_e32 v114, s18
	global_store_dword v114, v113, s[12:13] offset:20 sc1
.LBB0_98:
	s_or_b64 exec, exec, s[14:15]
	v_mul_f32_e32 v113, v61, v110
	s_waitcnt lgkmcnt(0)
	v_mul_f32_e32 v114, v63, v112
	v_fmac_f32_e32 v113, v60, v107
	v_fmac_f32_e32 v114, v62, v109
	v_add_f32_e32 v113, v113, v114
	v_mul_f32_e32 v114, v57, v111
	v_mul_f32_e32 v115, v59, v105
	v_fmac_f32_e32 v114, v56, v108
	v_fmac_f32_e32 v115, v58, v104
	v_add_f32_e32 v113, 0, v113
	v_add_f32_e32 v114, v114, v115
	v_add_f32_e32 v113, v114, v113
	v_mul_f32_e32 v114, v49, v106
	v_mul_f32_e32 v115, v51, v103
	v_fmac_f32_e32 v114, v48, v80
	v_fmac_f32_e32 v115, v50, v102
	v_add_f32_e32 v114, v114, v115
	v_add_f32_e32 v113, v114, v113
	v_mul_f32_e32 v114, v53, v100
	v_mul_f32_e32 v115, v55, v101
	v_fmac_f32_e32 v114, v52, v98
	v_fmac_f32_e32 v115, v54, v99
	v_add_f32_e32 v114, v114, v115
	v_add_f32_e32 v113, v114, v113
	s_waitcnt lgkmcnt(0)
	s_nop 1
	v_add_f32_dpp v113, v113, v113 quad_perm:[1,0,3,2] row_mask:0xf bank_mask:0xf
	s_nop 1
	v_add_f32_dpp v113, v113, v113 quad_perm:[2,3,0,1] row_mask:0xf bank_mask:0xf
	s_nop 1
	v_add_f32_dpp v113, v113, v113 row_half_mirror row_mask:0xf bank_mask:0xf
	s_nop 1
	v_add_f32_dpp v113, v113, v113 row_mirror row_mask:0xf bank_mask:0xf
	s_nop 1
	v_readlane_b32 s100, v113, 16
	v_readlane_b32 s101, v113, 32
	s_nop 1
	v_add_f32_e32 v114, s100, v113
	v_readlane_b32 s100, v113, 48
	v_add_f32_e32 v114, s101, v114
	s_nop 1
	v_add_f32_e32 v113, s100, v114
	s_and_saveexec_b64 s[14:15], s[38:39]
	s_cbranch_execz .LBB0_100
	v_mov_b32_e32 v114, s19
	global_store_dword v114, v113, s[12:13] offset:20 sc1
.LBB0_100:
	s_or_b64 exec, exec, s[14:15]
	v_mul_f32_e32 v113, v45, v110
	s_waitcnt lgkmcnt(0)
	v_mul_f32_e32 v114, v47, v112
	v_fmac_f32_e32 v113, v44, v107
	v_fmac_f32_e32 v114, v46, v109
	v_add_f32_e32 v113, v113, v114
	v_mul_f32_e32 v114, v41, v111
	v_mul_f32_e32 v115, v43, v105
	v_fmac_f32_e32 v114, v40, v108
	v_fmac_f32_e32 v115, v42, v104
	v_add_f32_e32 v113, 0, v113
	v_add_f32_e32 v114, v114, v115
	v_add_f32_e32 v113, v114, v113
	v_mul_f32_e32 v114, v33, v106
	v_mul_f32_e32 v115, v35, v103
	v_fmac_f32_e32 v114, v32, v80
	v_fmac_f32_e32 v115, v34, v102
	v_add_f32_e32 v114, v114, v115
	v_add_f32_e32 v113, v114, v113
	v_mul_f32_e32 v114, v37, v100
	v_mul_f32_e32 v115, v39, v101
	v_fmac_f32_e32 v114, v36, v98
	v_fmac_f32_e32 v115, v38, v99
	v_add_f32_e32 v114, v114, v115
	v_add_f32_e32 v113, v114, v113
	s_waitcnt lgkmcnt(0)
	s_nop 1
	v_add_f32_dpp v113, v113, v113 quad_perm:[1,0,3,2] row_mask:0xf bank_mask:0xf
	s_nop 1
	v_add_f32_dpp v113, v113, v113 quad_perm:[2,3,0,1] row_mask:0xf bank_mask:0xf
	s_nop 1
	v_add_f32_dpp v113, v113, v113 row_half_mirror row_mask:0xf bank_mask:0xf
	s_nop 1
	v_add_f32_dpp v113, v113, v113 row_mirror row_mask:0xf bank_mask:0xf
	s_nop 1
	v_readlane_b32 s100, v113, 16
	v_readlane_b32 s101, v113, 32
	s_nop 1
	v_add_f32_e32 v114, s100, v113
	v_readlane_b32 s100, v113, 48
	v_add_f32_e32 v114, s101, v114
	s_nop 1
	v_add_f32_e32 v113, s100, v114
	s_and_saveexec_b64 s[14:15], s[38:39]
	s_cbranch_execz .LBB0_102
	v_mov_b32_e32 v114, s26
	global_store_dword v114, v113, s[12:13] offset:20 sc1
.LBB0_102:
	s_or_b64 exec, exec, s[14:15]
	v_mul_f32_e32 v113, v29, v110
	s_waitcnt lgkmcnt(0)
	v_mul_f32_e32 v114, v31, v112
	v_fmac_f32_e32 v113, v28, v107
	v_fmac_f32_e32 v114, v30, v109
	v_add_f32_e32 v113, v113, v114
	v_mul_f32_e32 v114, v25, v111
	v_mul_f32_e32 v115, v27, v105
	v_fmac_f32_e32 v114, v24, v108
	v_fmac_f32_e32 v115, v26, v104
	v_add_f32_e32 v113, 0, v113
	v_add_f32_e32 v114, v114, v115
	v_add_f32_e32 v113, v114, v113
	v_mul_f32_e32 v114, v21, v106
	v_mul_f32_e32 v115, v23, v103
	v_fmac_f32_e32 v114, v20, v80
	v_fmac_f32_e32 v115, v22, v102
	v_add_f32_e32 v114, v114, v115
	v_add_f32_e32 v113, v114, v113
	v_mul_f32_e32 v114, v17, v100
	v_mul_f32_e32 v115, v19, v101
	v_fmac_f32_e32 v114, v16, v98
	v_fmac_f32_e32 v115, v18, v99
	v_add_f32_e32 v114, v114, v115
	v_add_f32_e32 v113, v114, v113
	s_waitcnt lgkmcnt(0)
	s_nop 1
	v_add_f32_dpp v113, v113, v113 quad_perm:[1,0,3,2] row_mask:0xf bank_mask:0xf
	s_nop 1
	v_add_f32_dpp v113, v113, v113 quad_perm:[2,3,0,1] row_mask:0xf bank_mask:0xf
	s_nop 1
	v_add_f32_dpp v113, v113, v113 row_half_mirror row_mask:0xf bank_mask:0xf
	s_nop 1
	v_add_f32_dpp v113, v113, v113 row_mirror row_mask:0xf bank_mask:0xf
	s_nop 1
	v_readlane_b32 s100, v113, 16
	v_readlane_b32 s101, v113, 32
	s_nop 1
	v_add_f32_e32 v114, s100, v113
	v_readlane_b32 s100, v113, 48
	v_add_f32_e32 v114, s101, v114
	s_nop 1
	v_add_f32_e32 v113, s100, v114
	s_and_saveexec_b64 s[14:15], s[38:39]
	s_cbranch_execz .LBB0_104
	v_mov_b32_e32 v114, s27
	global_store_dword v114, v113, s[12:13] offset:20 sc1
.LBB0_104:
	s_or_b64 exec, exec, s[14:15]
	v_mul_f32_e32 v110, v13, v110
	v_fmac_f32_e32 v110, v12, v107
	v_mul_f32_e32 v107, v15, v112
	v_fmac_f32_e32 v107, v14, v109
	v_mul_f32_e32 v109, v9, v111
	v_mul_f32_e32 v105, v11, v105
	v_fmac_f32_e32 v109, v8, v108
	v_fmac_f32_e32 v105, v10, v104
	v_add_f32_e32 v104, v109, v105
	v_mul_f32_e32 v105, v5, v106
	v_add_f32_e32 v107, v110, v107
	v_fmac_f32_e32 v105, v4, v80
	v_mul_f32_e32 v80, v7, v103
	v_mul_f32_e32 v100, v1, v100
	v_add_f32_e32 v107, 0, v107
	v_fmac_f32_e32 v80, v6, v102
	v_fmac_f32_e32 v100, v0, v98
	v_mul_f32_e32 v98, v3, v101
	v_add_f32_e32 v104, v104, v107
	v_add_f32_e32 v80, v105, v80
	v_fmac_f32_e32 v98, v2, v99
	v_add_f32_e32 v80, v80, v104
	v_add_f32_e32 v98, v100, v98
	v_add_f32_e32 v80, v98, v80
	s_waitcnt lgkmcnt(0)
	s_nop 1
	v_add_f32_dpp v80, v80, v80 quad_perm:[1,0,3,2] row_mask:0xf bank_mask:0xf
	s_nop 1
	v_add_f32_dpp v80, v80, v80 quad_perm:[2,3,0,1] row_mask:0xf bank_mask:0xf
	s_nop 1
	v_add_f32_dpp v80, v80, v80 row_half_mirror row_mask:0xf bank_mask:0xf
	s_nop 1
	v_add_f32_dpp v80, v80, v80 row_mirror row_mask:0xf bank_mask:0xf
	s_nop 1
	v_readlane_b32 s100, v80, 16
	v_readlane_b32 s101, v80, 32
	s_nop 1
	v_add_f32_e32 v98, s100, v80
	v_readlane_b32 s100, v80, 48
	v_add_f32_e32 v98, s101, v98
	s_nop 1
	v_add_f32_e32 v80, s100, v98
	s_and_saveexec_b64 s[14:15], s[38:39]
	s_cbranch_execz .LBB0_106
	v_mov_b32_e32 v98, s28
	global_store_dword v98, v80, s[12:13] offset:20 sc1
.LBB0_106:
	s_or_b64 exec, exec, s[14:15]
	v_and_b32_e32 v102, 0xffff0000, v94
	v_and_b32_e32 v104, 0xffff0000, v95
	v_lshlrev_b32_e32 v99, 16, v94
	v_lshlrev_b32_e32 v101, 16, v95
	v_mul_f32_e32 v105, v77, v102
	v_mul_f32_e32 v106, v79, v104
	v_lshlrev_b32_e32 v100, 16, v96
	v_and_b32_e32 v103, 0xffff0000, v96
	v_lshlrev_b32_e32 v96, 16, v97
	v_and_b32_e32 v97, 0xffff0000, v97
	v_fmac_f32_e32 v105, v76, v99
	v_fmac_f32_e32 v106, v78, v101
	v_add_f32_e32 v105, v105, v106
	v_mul_f32_e32 v106, v73, v103
	v_mul_f32_e32 v107, v75, v97
	v_fmac_f32_e32 v106, v72, v100
	v_fmac_f32_e32 v107, v74, v96
	s_waitcnt lgkmcnt(0)
	v_and_b32_e32 v98, 0xffff0000, v90
	v_and_b32_e32 v95, 0xffff0000, v91
	v_add_f32_e32 v105, 0, v105
	v_add_f32_e32 v106, v106, v107
	v_lshlrev_b32_e32 v80, 16, v90
	v_lshlrev_b32_e32 v94, 16, v91
	v_add_f32_e32 v105, v106, v105
	v_mul_f32_e32 v106, v69, v98
	v_mul_f32_e32 v107, v71, v95
	v_fmac_f32_e32 v106, v68, v80
	v_fmac_f32_e32 v107, v70, v94
	v_lshlrev_b32_e32 v90, 16, v92
	v_and_b32_e32 v92, 0xffff0000, v92
	v_lshlrev_b32_e32 v91, 16, v93
	v_and_b32_e32 v93, 0xffff0000, v93
	v_add_f32_e32 v106, v106, v107
	v_add_f32_e32 v105, v106, v105
	v_mul_f32_e32 v106, v65, v92
	v_mul_f32_e32 v107, v67, v93
	v_fmac_f32_e32 v106, v64, v90
	v_fmac_f32_e32 v107, v66, v91
	v_add_f32_e32 v106, v106, v107
	v_add_f32_e32 v105, v106, v105
	s_waitcnt lgkmcnt(0)
	s_nop 1
	v_add_f32_dpp v105, v105, v105 quad_perm:[1,0,3,2] row_mask:0xf bank_mask:0xf
	s_nop 1
	v_add_f32_dpp v105, v105, v105 quad_perm:[2,3,0,1] row_mask:0xf bank_mask:0xf
	s_nop 1
	v_add_f32_dpp v105, v105, v105 row_half_mirror row_mask:0xf bank_mask:0xf
	s_nop 1
	v_add_f32_dpp v105, v105, v105 row_mirror row_mask:0xf bank_mask:0xf
	s_nop 1
	v_readlane_b32 s100, v105, 16
	v_readlane_b32 s101, v105, 32
	s_nop 1
	v_add_f32_e32 v106, s100, v105
	v_readlane_b32 s100, v105, 48
	v_add_f32_e32 v106, s101, v106
	s_nop 1
	v_add_f32_e32 v105, s100, v106
	s_and_saveexec_b64 s[14:15], s[38:39]
	s_cbranch_execz .LBB0_108
	v_mov_b32_e32 v106, s18
	global_store_dword v106, v105, s[12:13] offset:24 sc1
.LBB0_108:
	s_or_b64 exec, exec, s[14:15]
	v_mul_f32_e32 v105, v61, v102
	s_waitcnt lgkmcnt(0)
	v_mul_f32_e32 v106, v63, v104
	v_fmac_f32_e32 v105, v60, v99
	v_fmac_f32_e32 v106, v62, v101
	v_add_f32_e32 v105, v105, v106
	v_mul_f32_e32 v106, v57, v103
	v_mul_f32_e32 v107, v59, v97
	v_fmac_f32_e32 v106, v56, v100
	v_fmac_f32_e32 v107, v58, v96
	v_add_f32_e32 v105, 0, v105
	v_add_f32_e32 v106, v106, v107
	v_add_f32_e32 v105, v106, v105
	v_mul_f32_e32 v106, v49, v98
	v_mul_f32_e32 v107, v51, v95
	v_fmac_f32_e32 v106, v48, v80
	v_fmac_f32_e32 v107, v50, v94
	v_add_f32_e32 v106, v106, v107
	v_add_f32_e32 v105, v106, v105
	v_mul_f32_e32 v106, v53, v92
	v_mul_f32_e32 v107, v55, v93
	v_fmac_f32_e32 v106, v52, v90
	v_fmac_f32_e32 v107, v54, v91
	v_add_f32_e32 v106, v106, v107
	v_add_f32_e32 v105, v106, v105
	s_waitcnt lgkmcnt(0)
	s_nop 1
	v_add_f32_dpp v105, v105, v105 quad_perm:[1,0,3,2] row_mask:0xf bank_mask:0xf
	s_nop 1
	v_add_f32_dpp v105, v105, v105 quad_perm:[2,3,0,1] row_mask:0xf bank_mask:0xf
	s_nop 1
	v_add_f32_dpp v105, v105, v105 row_half_mirror row_mask:0xf bank_mask:0xf
	s_nop 1
	v_add_f32_dpp v105, v105, v105 row_mirror row_mask:0xf bank_mask:0xf
	s_nop 1
	v_readlane_b32 s100, v105, 16
	v_readlane_b32 s101, v105, 32
	s_nop 1
	v_add_f32_e32 v106, s100, v105
	v_readlane_b32 s100, v105, 48
	v_add_f32_e32 v106, s101, v106
	s_nop 1
	v_add_f32_e32 v105, s100, v106
	s_and_saveexec_b64 s[14:15], s[38:39]
	s_cbranch_execz .LBB0_110
	v_mov_b32_e32 v106, s19
	global_store_dword v106, v105, s[12:13] offset:24 sc1
.LBB0_110:
	s_or_b64 exec, exec, s[14:15]
	v_mul_f32_e32 v105, v45, v102
	s_waitcnt lgkmcnt(0)
	v_mul_f32_e32 v106, v47, v104
	v_fmac_f32_e32 v105, v44, v99
	v_fmac_f32_e32 v106, v46, v101
	v_add_f32_e32 v105, v105, v106
	v_mul_f32_e32 v106, v41, v103
	v_mul_f32_e32 v107, v43, v97
	v_fmac_f32_e32 v106, v40, v100
	v_fmac_f32_e32 v107, v42, v96
	v_add_f32_e32 v105, 0, v105
	v_add_f32_e32 v106, v106, v107
	v_add_f32_e32 v105, v106, v105
	v_mul_f32_e32 v106, v33, v98
	v_mul_f32_e32 v107, v35, v95
	v_fmac_f32_e32 v106, v32, v80
	v_fmac_f32_e32 v107, v34, v94
	v_add_f32_e32 v106, v106, v107
	v_add_f32_e32 v105, v106, v105
	v_mul_f32_e32 v106, v37, v92
	v_mul_f32_e32 v107, v39, v93
	v_fmac_f32_e32 v106, v36, v90
	v_fmac_f32_e32 v107, v38, v91
	v_add_f32_e32 v106, v106, v107
	v_add_f32_e32 v105, v106, v105
	s_waitcnt lgkmcnt(0)
	s_nop 1
	v_add_f32_dpp v105, v105, v105 quad_perm:[1,0,3,2] row_mask:0xf bank_mask:0xf
	s_nop 1
	v_add_f32_dpp v105, v105, v105 quad_perm:[2,3,0,1] row_mask:0xf bank_mask:0xf
	s_nop 1
	v_add_f32_dpp v105, v105, v105 row_half_mirror row_mask:0xf bank_mask:0xf
	s_nop 1
	v_add_f32_dpp v105, v105, v105 row_mirror row_mask:0xf bank_mask:0xf
	s_nop 1
	v_readlane_b32 s100, v105, 16
	v_readlane_b32 s101, v105, 32
	s_nop 1
	v_add_f32_e32 v106, s100, v105
	v_readlane_b32 s100, v105, 48
	v_add_f32_e32 v106, s101, v106
	s_nop 1
	v_add_f32_e32 v105, s100, v106
	s_and_saveexec_b64 s[14:15], s[38:39]
	s_cbranch_execz .LBB0_112
	v_mov_b32_e32 v106, s26
	global_store_dword v106, v105, s[12:13] offset:24 sc1
.LBB0_112:
	s_or_b64 exec, exec, s[14:15]
	v_mul_f32_e32 v105, v29, v102
	s_waitcnt lgkmcnt(0)
	v_mul_f32_e32 v106, v31, v104
	v_fmac_f32_e32 v105, v28, v99
	v_fmac_f32_e32 v106, v30, v101
	v_add_f32_e32 v105, v105, v106
	v_mul_f32_e32 v106, v25, v103
	v_mul_f32_e32 v107, v27, v97
	v_fmac_f32_e32 v106, v24, v100
	v_fmac_f32_e32 v107, v26, v96
	v_add_f32_e32 v105, 0, v105
	v_add_f32_e32 v106, v106, v107
	v_add_f32_e32 v105, v106, v105
	v_mul_f32_e32 v106, v21, v98
	v_mul_f32_e32 v107, v23, v95
	v_fmac_f32_e32 v106, v20, v80
	v_fmac_f32_e32 v107, v22, v94
	v_add_f32_e32 v106, v106, v107
	v_add_f32_e32 v105, v106, v105
	v_mul_f32_e32 v106, v17, v92
	v_mul_f32_e32 v107, v19, v93
	v_fmac_f32_e32 v106, v16, v90
	v_fmac_f32_e32 v107, v18, v91
	v_add_f32_e32 v106, v106, v107
	v_add_f32_e32 v105, v106, v105
	s_waitcnt lgkmcnt(0)
	s_nop 1
	v_add_f32_dpp v105, v105, v105 quad_perm:[1,0,3,2] row_mask:0xf bank_mask:0xf
	s_nop 1
	v_add_f32_dpp v105, v105, v105 quad_perm:[2,3,0,1] row_mask:0xf bank_mask:0xf
	s_nop 1
	v_add_f32_dpp v105, v105, v105 row_half_mirror row_mask:0xf bank_mask:0xf
	s_nop 1
	v_add_f32_dpp v105, v105, v105 row_mirror row_mask:0xf bank_mask:0xf
	s_nop 1
	v_readlane_b32 s100, v105, 16
	v_readlane_b32 s101, v105, 32
	s_nop 1
	v_add_f32_e32 v106, s100, v105
	v_readlane_b32 s100, v105, 48
	v_add_f32_e32 v106, s101, v106
	s_nop 1
	v_add_f32_e32 v105, s100, v106
	s_and_saveexec_b64 s[14:15], s[38:39]
	s_cbranch_execz .LBB0_114
	v_mov_b32_e32 v106, s27
	global_store_dword v106, v105, s[12:13] offset:24 sc1
.LBB0_114:
	s_or_b64 exec, exec, s[14:15]
	v_mul_f32_e32 v102, v13, v102
	v_fmac_f32_e32 v102, v12, v99
	v_mul_f32_e32 v99, v15, v104
	v_fmac_f32_e32 v99, v14, v101
	v_mul_f32_e32 v101, v9, v103
	v_mul_f32_e32 v97, v11, v97
	v_fmac_f32_e32 v101, v8, v100
	v_fmac_f32_e32 v97, v10, v96
	v_add_f32_e32 v96, v101, v97
	v_mul_f32_e32 v97, v5, v98
	v_add_f32_e32 v99, v102, v99
	v_fmac_f32_e32 v97, v4, v80
	v_mul_f32_e32 v80, v7, v95
	v_mul_f32_e32 v92, v1, v92
	v_add_f32_e32 v99, 0, v99
	v_fmac_f32_e32 v80, v6, v94
	v_fmac_f32_e32 v92, v0, v90
	v_mul_f32_e32 v90, v3, v93
	v_add_f32_e32 v96, v96, v99
	v_add_f32_e32 v80, v97, v80
	v_fmac_f32_e32 v90, v2, v91
	v_add_f32_e32 v80, v80, v96
	v_add_f32_e32 v90, v92, v90
	v_add_f32_e32 v80, v90, v80
	s_waitcnt lgkmcnt(0)
	s_nop 1
	v_add_f32_dpp v80, v80, v80 quad_perm:[1,0,3,2] row_mask:0xf bank_mask:0xf
	s_nop 1
	v_add_f32_dpp v80, v80, v80 quad_perm:[2,3,0,1] row_mask:0xf bank_mask:0xf
	s_nop 1
	v_add_f32_dpp v80, v80, v80 row_half_mirror row_mask:0xf bank_mask:0xf
	s_nop 1
	v_add_f32_dpp v80, v80, v80 row_mirror row_mask:0xf bank_mask:0xf
	s_nop 1
	v_readlane_b32 s100, v80, 16
	v_readlane_b32 s101, v80, 32
	s_nop 1
	v_add_f32_e32 v90, s100, v80
	v_readlane_b32 s100, v80, 48
	v_add_f32_e32 v90, s101, v90
	s_nop 1
	v_add_f32_e32 v80, s100, v90
	s_and_saveexec_b64 s[14:15], s[38:39]
	s_cbranch_execz .LBB0_116
	v_mov_b32_e32 v90, s28
	global_store_dword v90, v80, s[12:13] offset:24 sc1
.LBB0_116:
	s_or_b64 exec, exec, s[14:15]
	s_waitcnt vmcnt(0)
	v_and_b32_e32 v94, 0xffff0000, v86
	v_lshlrev_b32_e32 v91, 16, v86
	v_and_b32_e32 v96, 0xffff0000, v87
	v_and_b32_e32 v95, 0xffff0000, v88
	v_mul_f32_e32 v77, v77, v94
	s_waitcnt lgkmcnt(0)
	v_and_b32_e32 v90, 0xffff0000, v82
	v_lshlrev_b32_e32 v93, 16, v87
	v_lshlrev_b32_e32 v92, 16, v88
	v_lshlrev_b32_e32 v88, 16, v89
	v_and_b32_e32 v89, 0xffff0000, v89
	v_fmac_f32_e32 v77, v76, v91
	v_mul_f32_e32 v76, v79, v96
	v_mul_f32_e32 v73, v73, v95
	v_lshlrev_b32_e32 v80, 16, v82
	v_and_b32_e32 v87, 0xffff0000, v83
	v_lshlrev_b32_e32 v82, 16, v84
	v_and_b32_e32 v84, 0xffff0000, v84
	v_fmac_f32_e32 v76, v78, v93
	v_fmac_f32_e32 v73, v72, v92
	v_mul_f32_e32 v72, v75, v89
	v_mul_f32_e32 v69, v69, v90
	v_lshlrev_b32_e32 v86, 16, v83
	v_lshlrev_b32_e32 v83, 16, v85
	v_and_b32_e32 v85, 0xffff0000, v85
	v_add_f32_e32 v76, v77, v76
	v_fmac_f32_e32 v72, v74, v88
	v_fmac_f32_e32 v69, v68, v80
	v_mul_f32_e32 v68, v71, v87
	v_mul_f32_e32 v65, v65, v84
	v_add_f32_e32 v76, 0, v76
	v_add_f32_e32 v72, v73, v72
	v_fmac_f32_e32 v68, v70, v86
	v_fmac_f32_e32 v65, v64, v82
	v_mul_f32_e32 v64, v67, v85
	v_add_f32_e32 v72, v72, v76
	v_add_f32_e32 v68, v69, v68
	v_fmac_f32_e32 v64, v66, v83
	v_add_f32_e32 v68, v68, v72
	v_add_f32_e32 v64, v65, v64
	v_add_f32_e32 v64, v64, v68
	s_waitcnt lgkmcnt(0)
	s_nop 1
	v_add_f32_dpp v64, v64, v64 quad_perm:[1,0,3,2] row_mask:0xf bank_mask:0xf
	s_nop 1
	v_add_f32_dpp v64, v64, v64 quad_perm:[2,3,0,1] row_mask:0xf bank_mask:0xf
	s_nop 1
	v_add_f32_dpp v64, v64, v64 row_half_mirror row_mask:0xf bank_mask:0xf
	s_nop 1
	v_add_f32_dpp v64, v64, v64 row_mirror row_mask:0xf bank_mask:0xf
	s_nop 1
	v_readlane_b32 s100, v64, 16
	v_readlane_b32 s101, v64, 32
	s_nop 1
	v_add_f32_e32 v65, s100, v64
	v_readlane_b32 s100, v64, 48
	v_add_f32_e32 v65, s101, v65
	s_nop 1
	v_add_f32_e32 v64, s100, v65
	s_and_saveexec_b64 s[14:15], s[38:39]
	s_cbranch_execz .LBB0_118
	v_mov_b32_e32 v65, s18
	global_store_dword v65, v64, s[12:13] offset:28 sc1
.LBB0_118:
	s_or_b64 exec, exec, s[14:15]
	v_mul_f32_e32 v61, v61, v94
	v_fmac_f32_e32 v61, v60, v91
	v_mul_f32_e32 v60, v63, v96
	v_mul_f32_e32 v57, v57, v95
	v_mul_f32_e32 v49, v49, v90
	v_fmac_f32_e32 v60, v62, v93
	v_fmac_f32_e32 v57, v56, v92
	v_mul_f32_e32 v56, v59, v89
	v_fmac_f32_e32 v49, v48, v80
	v_mul_f32_e32 v48, v51, v87
	v_add_f32_e32 v60, v61, v60
	v_fmac_f32_e32 v56, v58, v88
	v_fmac_f32_e32 v48, v50, v86
	v_add_f32_e32 v60, 0, v60
	v_add_f32_e32 v56, v57, v56
	v_add_f32_e32 v48, v49, v48
	v_mul_f32_e32 v49, v53, v84
	v_mul_f32_e32 v50, v55, v85
	v_add_f32_e32 v56, v56, v60
	v_fmac_f32_e32 v49, v52, v82
	v_fmac_f32_e32 v50, v54, v83
	v_add_f32_e32 v48, v48, v56
	v_add_f32_e32 v49, v49, v50
	v_add_f32_e32 v48, v49, v48
	s_waitcnt lgkmcnt(0)
	s_nop 1
	v_add_f32_dpp v48, v48, v48 quad_perm:[1,0,3,2] row_mask:0xf bank_mask:0xf
	s_nop 1
	v_add_f32_dpp v48, v48, v48 quad_perm:[2,3,0,1] row_mask:0xf bank_mask:0xf
	s_nop 1
	v_add_f32_dpp v48, v48, v48 row_half_mirror row_mask:0xf bank_mask:0xf
	s_nop 1
	v_add_f32_dpp v48, v48, v48 row_mirror row_mask:0xf bank_mask:0xf
	s_nop 1
	v_readlane_b32 s100, v48, 16
	v_readlane_b32 s101, v48, 32
	s_nop 1
	v_add_f32_e32 v49, s100, v48
	v_readlane_b32 s100, v48, 48
	v_add_f32_e32 v49, s101, v49
	s_nop 1
	v_add_f32_e32 v48, s100, v49
	s_and_saveexec_b64 s[14:15], s[38:39]
	s_cbranch_execz .LBB0_120
	v_mov_b32_e32 v49, s19
	global_store_dword v49, v48, s[12:13] offset:28 sc1
.LBB0_120:
	s_or_b64 exec, exec, s[14:15]
	v_mul_f32_e32 v45, v45, v94
	v_fmac_f32_e32 v45, v44, v91
	v_mul_f32_e32 v44, v47, v96
	v_mul_f32_e32 v41, v41, v95
	v_mul_f32_e32 v33, v33, v90
	v_fmac_f32_e32 v44, v46, v93
	v_fmac_f32_e32 v41, v40, v92
	v_mul_f32_e32 v40, v43, v89
	v_fmac_f32_e32 v33, v32, v80
	v_mul_f32_e32 v32, v35, v87
	v_add_f32_e32 v44, v45, v44
	v_fmac_f32_e32 v40, v42, v88
	v_fmac_f32_e32 v32, v34, v86
	v_add_f32_e32 v44, 0, v44
	v_add_f32_e32 v40, v41, v40
	v_add_f32_e32 v32, v33, v32
	v_mul_f32_e32 v33, v37, v84
	v_mul_f32_e32 v34, v39, v85
	v_add_f32_e32 v40, v40, v44
	v_fmac_f32_e32 v33, v36, v82
	v_fmac_f32_e32 v34, v38, v83
	v_add_f32_e32 v32, v32, v40
	v_add_f32_e32 v33, v33, v34
	v_add_f32_e32 v32, v33, v32
	s_waitcnt lgkmcnt(0)
	s_nop 1
	v_add_f32_dpp v32, v32, v32 quad_perm:[1,0,3,2] row_mask:0xf bank_mask:0xf
	s_nop 1
	v_add_f32_dpp v32, v32, v32 quad_perm:[2,3,0,1] row_mask:0xf bank_mask:0xf
	s_nop 1
	v_add_f32_dpp v32, v32, v32 row_half_mirror row_mask:0xf bank_mask:0xf
	s_nop 1
	v_add_f32_dpp v32, v32, v32 row_mirror row_mask:0xf bank_mask:0xf
	s_nop 1
	v_readlane_b32 s100, v32, 16
	v_readlane_b32 s101, v32, 32
	s_nop 1
	v_add_f32_e32 v33, s100, v32
	v_readlane_b32 s100, v32, 48
	v_add_f32_e32 v33, s101, v33
	s_nop 1
	v_add_f32_e32 v32, s100, v33
	s_and_saveexec_b64 s[14:15], s[38:39]
	s_cbranch_execz .LBB0_122
	v_mov_b32_e32 v33, s26
	global_store_dword v33, v32, s[12:13] offset:28 sc1
.LBB0_122:
	s_or_b64 exec, exec, s[14:15]
	v_mul_f32_e32 v29, v29, v94
	v_fmac_f32_e32 v29, v28, v91
	v_mul_f32_e32 v28, v31, v96
	v_mul_f32_e32 v25, v25, v95
	v_fmac_f32_e32 v28, v30, v93
	v_fmac_f32_e32 v25, v24, v92
	v_mul_f32_e32 v24, v27, v89
	v_mul_f32_e32 v21, v21, v90
	v_add_f32_e32 v28, v29, v28
	v_fmac_f32_e32 v24, v26, v88
	v_fmac_f32_e32 v21, v20, v80
	v_mul_f32_e32 v20, v23, v87
	v_mul_f32_e32 v17, v17, v84
	v_add_f32_e32 v28, 0, v28
	v_add_f32_e32 v24, v25, v24
	v_fmac_f32_e32 v20, v22, v86
	v_fmac_f32_e32 v17, v16, v82
	v_mul_f32_e32 v16, v19, v85
	v_add_f32_e32 v24, v24, v28
	v_add_f32_e32 v20, v21, v20
	v_fmac_f32_e32 v16, v18, v83
	v_add_f32_e32 v20, v20, v24
	v_add_f32_e32 v16, v17, v16
	v_add_f32_e32 v16, v16, v20
	s_waitcnt lgkmcnt(0)
	s_nop 1
	v_add_f32_dpp v16, v16, v16 quad_perm:[1,0,3,2] row_mask:0xf bank_mask:0xf
	s_nop 1
	v_add_f32_dpp v16, v16, v16 quad_perm:[2,3,0,1] row_mask:0xf bank_mask:0xf
	s_nop 1
	v_add_f32_dpp v16, v16, v16 row_half_mirror row_mask:0xf bank_mask:0xf
	s_nop 1
	v_add_f32_dpp v16, v16, v16 row_mirror row_mask:0xf bank_mask:0xf
	s_nop 1
	v_readlane_b32 s100, v16, 16
	v_readlane_b32 s101, v16, 32
	s_nop 1
	v_add_f32_e32 v17, s100, v16
	v_readlane_b32 s100, v16, 48
	v_add_f32_e32 v17, s101, v17
	s_nop 1
	v_add_f32_e32 v16, s100, v17
	s_and_saveexec_b64 s[14:15], s[38:39]
	s_cbranch_execz .LBB0_124
	v_mov_b32_e32 v17, s27
	global_store_dword v17, v16, s[12:13] offset:28 sc1
.LBB0_124:
	s_or_b64 exec, exec, s[14:15]
	v_mul_f32_e32 v13, v13, v94
	v_fmac_f32_e32 v13, v12, v91
	v_mul_f32_e32 v12, v15, v96
	v_mul_f32_e32 v9, v9, v95
	v_fmac_f32_e32 v12, v14, v93
	v_fmac_f32_e32 v9, v8, v92
	v_mul_f32_e32 v8, v11, v89
	v_mul_f32_e32 v5, v5, v90
	v_add_f32_e32 v12, v13, v12
	v_fmac_f32_e32 v8, v10, v88
	v_fmac_f32_e32 v5, v4, v80
	v_mul_f32_e32 v4, v7, v87
	v_mul_f32_e32 v1, v1, v84
	v_add_f32_e32 v12, 0, v12
	v_add_f32_e32 v8, v9, v8
	v_fmac_f32_e32 v4, v6, v86
	v_fmac_f32_e32 v1, v0, v82
	v_mul_f32_e32 v0, v3, v85
	v_add_f32_e32 v8, v8, v12
	v_add_f32_e32 v4, v5, v4
	v_fmac_f32_e32 v0, v2, v83
	v_add_f32_e32 v4, v4, v8
	v_add_f32_e32 v0, v1, v0
	v_add_f32_e32 v0, v0, v4
	s_waitcnt lgkmcnt(0)
	s_nop 1
	v_add_f32_dpp v0, v0, v0 quad_perm:[1,0,3,2] row_mask:0xf bank_mask:0xf
	s_nop 1
	v_add_f32_dpp v0, v0, v0 quad_perm:[2,3,0,1] row_mask:0xf bank_mask:0xf
	s_nop 1
	v_add_f32_dpp v0, v0, v0 row_half_mirror row_mask:0xf bank_mask:0xf
	s_nop 1
	v_add_f32_dpp v0, v0, v0 row_mirror row_mask:0xf bank_mask:0xf
	s_nop 1
	v_readlane_b32 s100, v0, 16
	v_readlane_b32 s101, v0, 32
	s_nop 1
	v_add_f32_e32 v1, s100, v0
	v_readlane_b32 s100, v0, 48
	v_add_f32_e32 v1, s101, v1
	s_nop 1
	v_add_f32_e32 v0, s100, v1
	s_and_saveexec_b64 s[14:15], s[38:39]
	s_cbranch_execz .LBB0_126
	v_mov_b32_e32 v1, s28
	global_store_dword v1, v0, s[12:13] offset:28 sc1
